# nt hint on the read-once row loads of phases I and L (x, x1, MIX, F rows)
# speedup vs baseline: 1.0196x; 1.0058x over previous
.LBB0_1512:
	v_add_co_u32_e32 v4, vcc, 0xfffff000, v70
	v_mov_b32_e32 v77, v137
	s_nop 0
	v_addc_co_u32_e32 v5, vcc, -1, v71, vcc
	v_add_co_u32_e32 v80, vcc, 0xffffd000, v68
	global_load_dwordx2 v[118:119], v[4:5], off offset:-3584 nt
	s_nop 0
	v_addc_co_u32_e32 v81, vcc, -1, v69, vcc
	global_load_dwordx4 v[48:51], v[80:81], off offset:-3072 nt
	global_load_dwordx2 v[110:111], v[4:5], off offset:-3072 nt
	global_load_dwordx4 v[32:35], v[80:81], off offset:-2048 nt
	global_load_dwordx2 v[112:113], v[4:5], off offset:-2560 nt
	global_load_dwordx4 v[16:19], v[80:81], off offset:-1024 nt
	global_load_dwordx2 v[0:1], v[4:5], off offset:-2048 nt
	v_add_co_u32_e32 v82, vcc, s80, v68
	v_mov_b32_e32 v79, v137
	s_nop 0
	v_addc_co_u32_e32 v83, vcc, -1, v69, vcc
	v_add_co_u32_e32 v108, vcc, s33, v68
	s_movk_i32 s2, 0x3fff
	s_nop 0
	v_addc_co_u32_e32 v109, vcc, -1, v69, vcc
	s_waitcnt vmcnt(4)
	v_and_b32_e32 v121, 0xffff0000, v111
	v_and_b32_e32 v149, 0xffff0000, v119
	v_and_b32_e32 v147, 0xffff0000, v118
	v_lshlrev_b32_e32 v148, 16, v119
	s_waitcnt vmcnt(0)
	v_lshlrev_b32_e32 v89, 16, v0
	v_and_b32_e32 v87, 0xffff0000, v0
	v_lshlrev_b32_e32 v84, 16, v1
	v_and_b32_e32 v85, 0xffff0000, v1
	global_load_dwordx4 v[0:3], v[80:81], off nt
	global_load_dwordx2 v[122:123], v[4:5], off offset:-1536 nt
	global_load_dwordx4 v[52:55], v[82:83], off offset:-3072 nt
	global_load_dwordx2 v[114:115], v[4:5], off offset:-1024 nt
	global_load_dwordx4 v[36:39], v[82:83], off offset:-2048 nt
	global_load_dwordx2 v[116:117], v[4:5], off offset:-512 nt
	global_load_dwordx4 v[20:23], v[82:83], off offset:-1024 nt
	s_nop 0
	global_load_dwordx2 v[4:5], v[70:71], off offset:-4096 nt
	v_mul_f32_e32 v86, v149, v149
	v_lshlrev_b32_e32 v146, 16, v118
	v_pk_fma_f32 v[124:125], v[148:149], v[148:149], v[86:87] op_sel_hi:[1,1,0]
	v_and_b32_e32 v120, 0xffff0000, v110
	v_mul_f32_e32 v86, v147, v147
	v_lshlrev_b32_e32 v119, 16, v111
	v_lshlrev_b32_e32 v118, 16, v110
	v_pk_mul_f32 v[110:111], v[120:121], v[120:121]
	v_pk_fma_f32 v[138:139], v[146:147], v[146:147], v[86:87] op_sel_hi:[1,1,0]
	v_pk_fma_f32 v[134:135], v[118:119], v[118:119], v[110:111]
	v_mov_b32_e32 v88, v138
	v_mov_b32_e32 v144, v124
	v_mov_b32_e32 v145, v89
	v_and_b32_e32 v111, 0xffff0000, v112
	v_mul_f32_e32 v65, v87, v87
	v_pk_add_f32 v[124:125], v[138:139], v[124:125]
	v_pk_mul_f32 v[138:139], v[88:89], v[144:145]
	v_pk_add_f32 v[134:135], v[134:135], v[134:135] op_sel:[0,1] op_sel_hi:[1,0]
	v_lshlrev_b32_e32 v110, 16, v112
	v_lshlrev_b32_e32 v112, 16, v113
	v_and_b32_e32 v113, 0xffff0000, v113
	v_mov_b32_e32 v125, v139
	v_mov_b32_e32 v135, v65
	v_mul_f32_e32 v86, v111, v111
	v_pk_add_f32 v[124:125], v[124:125], v[134:135]
	v_pk_fma_f32 v[134:135], v[110:111], v[110:111], v[86:87] op_sel_hi:[1,1,0]
	v_mul_f32_e32 v86, v113, v113
	v_mul_f32_e32 v73, v84, v84
	v_mul_f32_e32 v75, v85, v85
	v_pk_fma_f32 v[138:139], v[112:113], v[112:113], v[86:87] op_sel_hi:[1,1,0]
	v_mov_b32_e32 v135, v73
	v_mov_b32_e32 v139, v75
	v_pk_add_f32 v[134:135], v[134:135], v[138:139]
	s_waitcnt vmcnt(6)
	v_and_b32_e32 v153, 0xffff0000, v123
	s_waitcnt vmcnt(0)
	v_lshlrev_b32_e32 v95, 16, v4
	v_and_b32_e32 v93, 0xffff0000, v4
	v_lshlrev_b32_e32 v90, 16, v5
	v_and_b32_e32 v91, 0xffff0000, v5
	global_load_dwordx4 v[4:7], v[82:83], off nt
	global_load_dwordx2 v[130:131], v[70:71], off offset:-3584 nt
	global_load_dwordx4 v[56:59], v[108:109], off offset:-3072 nt
	global_load_dwordx2 v[126:127], v[70:71], off offset:-3072 nt
	global_load_dwordx4 v[40:43], v[108:109], off offset:-2048 nt
	global_load_dwordx2 v[128:129], v[70:71], off offset:-2560 nt
	global_load_dwordx4 v[24:27], v[108:109], off offset:-1024 nt
	global_load_dwordx2 v[8:9], v[70:71], off offset:-2048 nt
	v_and_b32_e32 v151, 0xffff0000, v122
	v_lshlrev_b32_e32 v152, 16, v123
	v_mul_f32_e32 v86, v153, v153
	v_pk_add_f32 v[134:135], v[124:125], v[134:135]
	v_lshlrev_b32_e32 v150, 16, v122
	v_pk_fma_f32 v[138:139], v[152:153], v[152:153], v[86:87] op_sel_hi:[1,1,0]
	v_and_b32_e32 v125, 0xffff0000, v115
	v_and_b32_e32 v124, 0xffff0000, v114
	v_mul_f32_e32 v86, v151, v151
	v_lshlrev_b32_e32 v123, 16, v115
	v_lshlrev_b32_e32 v122, 16, v114
	v_pk_mul_f32 v[114:115], v[124:125], v[124:125]
	v_pk_fma_f32 v[154:155], v[150:151], v[150:151], v[86:87] op_sel_hi:[1,1,0]
	v_pk_fma_f32 v[144:145], v[122:123], v[122:123], v[114:115]
	v_mov_b32_e32 v94, v154
	v_mov_b32_e32 v156, v138
	v_mov_b32_e32 v157, v95
	v_and_b32_e32 v115, 0xffff0000, v116
	v_mul_f32_e32 v65, v93, v93
	v_pk_add_f32 v[138:139], v[154:155], v[138:139]
	v_pk_mul_f32 v[154:155], v[94:95], v[156:157]
	v_pk_add_f32 v[144:145], v[144:145], v[144:145] op_sel:[0,1] op_sel_hi:[1,0]
	v_lshlrev_b32_e32 v114, 16, v116
	v_lshlrev_b32_e32 v116, 16, v117
	v_and_b32_e32 v117, 0xffff0000, v117
	v_mov_b32_e32 v139, v155
	v_mov_b32_e32 v145, v65
	v_mul_f32_e32 v86, v115, v115
	v_pk_add_f32 v[138:139], v[138:139], v[144:145]
	v_pk_fma_f32 v[144:145], v[114:115], v[114:115], v[86:87] op_sel_hi:[1,1,0]
	v_mul_f32_e32 v86, v117, v117
	v_mul_f32_e32 v73, v90, v90
	v_mul_f32_e32 v75, v91, v91
	v_pk_fma_f32 v[154:155], v[116:117], v[116:117], v[86:87] op_sel_hi:[1,1,0]
	v_mov_b32_e32 v145, v73
	v_mov_b32_e32 v155, v75
	v_pk_add_f32 v[144:145], v[144:145], v[154:155]
	s_waitcnt vmcnt(6)
	v_and_b32_e32 v157, 0xffff0000, v131
	s_waitcnt vmcnt(0)
	v_lshlrev_b32_e32 v101, 16, v8
	v_and_b32_e32 v99, 0xffff0000, v8
	v_lshlrev_b32_e32 v96, 16, v9
	v_and_b32_e32 v97, 0xffff0000, v9
	global_load_dwordx4 v[8:11], v[68:69], off offset:-4096 nt
	global_load_dwordx2 v[140:141], v[70:71], off offset:-1536 nt
	global_load_dwordx4 v[60:63], v[68:69], off offset:-3072 nt
	global_load_dwordx2 v[142:143], v[70:71], off offset:-1024 nt
	global_load_dwordx4 v[44:47], v[68:69], off offset:-2048 nt
	global_load_dwordx2 v[132:133], v[70:71], off offset:-512 nt
	global_load_dwordx4 v[28:31], v[68:69], off offset:-1024 nt
	global_load_dwordx2 v[12:13], v[70:71], off nt
	v_pk_add_f32 v[138:139], v[138:139], v[144:145]
	v_mov_b32_e32 v145, v134
	v_mov_b32_e32 v144, v138
	v_mov_b32_e32 v134, v139
	v_pk_add_f32 v[134:135], v[144:145], v[134:135]
	ds_bpermute_b32 v139, v162, v135
	ds_bpermute_b32 v138, v162, v134
	v_mov_b64_e32 v[144:145], s[90:91]
	v_and_b32_e32 v155, 0xffff0000, v130
	v_lshlrev_b32_e32 v156, 16, v131
	v_mul_f32_e32 v86, v157, v157
	s_waitcnt lgkmcnt(0)
	v_pk_add_f32 v[134:135], v[134:135], v[138:139]
	ds_bpermute_b32 v139, v163, v135
	ds_bpermute_b32 v138, v163, v134
	v_lshlrev_b32_e32 v154, 16, v130
	v_pk_fma_f32 v[130:131], v[156:157], v[156:157], v[86:87] op_sel_hi:[1,1,0]
	v_mul_f32_e32 v86, v155, v155
	v_pk_fma_f32 v[160:161], v[154:155], v[154:155], v[86:87] op_sel_hi:[1,1,0]
	s_waitcnt lgkmcnt(0)
	v_pk_add_f32 v[134:135], v[134:135], v[138:139]
	ds_bpermute_b32 v139, v164, v135
	ds_bpermute_b32 v138, v164, v134
	v_mov_b32_e32 v100, v160
	v_mov_b32_e32 v168, v130
	v_mov_b32_e32 v169, v101
	v_pk_add_f32 v[130:131], v[160:161], v[130:131]
	s_waitcnt lgkmcnt(0)
	v_pk_add_f32 v[134:135], v[134:135], v[138:139]
	ds_bpermute_b32 v139, v165, v135
	ds_bpermute_b32 v138, v165, v134
	v_pk_mul_f32 v[160:161], v[100:101], v[168:169]
	v_mul_f32_e32 v75, v97, v97
	v_mov_b32_e32 v131, v161
	v_mov_b32_e32 v98, v101
	s_waitcnt lgkmcnt(0)
	v_pk_add_f32 v[134:135], v[134:135], v[138:139]
	ds_bpermute_b32 v139, v166, v135
	ds_bpermute_b32 v138, v166, v134
	v_lshl_add_u64 v[70:71], v[70:71], 0, s[76:77]
	s_waitcnt lgkmcnt(0)
	v_pk_add_f32 v[134:135], v[134:135], v[138:139]
	ds_bpermute_b32 v139, v167, v135
	ds_bpermute_b32 v138, v167, v134
	s_waitcnt lgkmcnt(0)
	v_pk_add_f32 v[134:135], v[134:135], v[138:139]
	s_nop 0
	v_pk_fma_f32 v[134:135], v[134:135], s[82:83], v[144:145] op_sel_hi:[1,0,0]
	v_and_b32_e32 v139, 0xffff0000, v127
	v_mul_f32_e32 v65, 0x4b800000, v135
	v_cmp_gt_f32_e64 s[4:5], s81, v135
	v_cmp_gt_f32_e32 vcc, s81, v134
	v_and_b32_e32 v138, 0xffff0000, v126
	v_cndmask_b32_e64 v65, v135, v65, s[4:5]
	v_rsq_f32_e32 v65, v65
	v_lshlrev_b32_e32 v135, 16, v127
	v_mul_f32_e32 v73, 0x45800000, v65
	v_cndmask_b32_e64 v92, v65, v73, s[4:5]
	v_mul_f32_e32 v65, 0x4b800000, v134
	v_cndmask_b32_e32 v65, v134, v65, vcc
	v_rsq_f32_e32 v65, v65
	v_lshlrev_b32_e32 v134, 16, v126
	v_pk_mul_f32 v[126:127], v[138:139], v[138:139]
	v_pk_mul_f32 v[148:149], v[92:93], v[148:149] op_sel_hi:[0,1]
	v_mul_f32_e32 v73, 0x45800000, v65
	v_pk_fma_f32 v[158:159], v[134:135], v[134:135], v[126:127]
	v_cndmask_b32_e32 v88, v65, v73, vcc
	v_and_b32_e32 v127, 0xffff0000, v128
	v_mul_f32_e32 v65, v99, v99
	v_pk_add_f32 v[158:159], v[158:159], v[158:159] op_sel:[0,1] op_sel_hi:[1,0]
	v_lshlrev_b32_e32 v126, 16, v128
	v_lshlrev_b32_e32 v128, 16, v129
	v_and_b32_e32 v129, 0xffff0000, v129
	v_mov_b32_e32 v159, v65
	v_mul_f32_e32 v86, v127, v127
	v_pk_add_f32 v[130:131], v[130:131], v[158:159]
	v_pk_fma_f32 v[158:159], v[126:127], v[126:127], v[86:87] op_sel_hi:[1,1,0]
	v_mul_f32_e32 v86, v129, v129
	v_mul_f32_e32 v73, v96, v96
	v_pk_fma_f32 v[160:161], v[128:129], v[128:129], v[86:87] op_sel_hi:[1,1,0]
	v_mov_b32_e32 v159, v73
	v_mov_b32_e32 v161, v75
	v_pk_add_f32 v[158:159], v[158:159], v[160:161]
	s_waitcnt vmcnt(6)
	v_and_b32_e32 v161, 0xffff0000, v141
	v_pk_add_f32 v[168:169], v[130:131], v[158:159]
	v_and_b32_e32 v159, 0xffff0000, v140
	v_lshlrev_b32_e32 v160, 16, v141
	v_mul_f32_e32 v86, v161, v161
	v_lshlrev_b32_e32 v158, 16, v140
	v_pk_fma_f32 v[170:171], v[160:161], v[160:161], v[86:87] op_sel_hi:[1,1,0]
	s_waitcnt vmcnt(4)
	v_lshlrev_b32_e32 v141, 16, v143
	v_lshlrev_b32_e32 v140, 16, v142
	v_and_b32_e32 v143, 0xffff0000, v143
	v_and_b32_e32 v142, 0xffff0000, v142
	v_mul_f32_e32 v86, v159, v159
	s_waitcnt vmcnt(0)
	v_lshlrev_b32_e32 v107, 16, v12
	v_pk_mul_f32 v[130:131], v[142:143], v[142:143]
	v_pk_fma_f32 v[188:189], v[158:159], v[158:159], v[86:87] op_sel_hi:[1,1,0]
	v_and_b32_e32 v105, 0xffff0000, v12
	v_pk_fma_f32 v[172:173], v[140:141], v[140:141], v[130:131]
	v_mov_b32_e32 v106, v188
	v_mov_b32_e32 v190, v170
	v_mov_b32_e32 v191, v107
	v_and_b32_e32 v131, 0xffff0000, v132
	v_mul_f32_e32 v65, v105, v105
	v_pk_add_f32 v[170:171], v[188:189], v[170:171]
	v_pk_mul_f32 v[188:189], v[106:107], v[190:191]
	v_pk_add_f32 v[172:173], v[172:173], v[172:173] op_sel:[0,1] op_sel_hi:[1,0]
	v_lshlrev_b32_e32 v130, 16, v132
	v_lshlrev_b32_e32 v132, 16, v133
	v_and_b32_e32 v133, 0xffff0000, v133
	v_mov_b32_e32 v171, v189
	v_mov_b32_e32 v173, v65
	v_mul_f32_e32 v86, v131, v131
	v_lshlrev_b32_e32 v102, 16, v13
	v_and_b32_e32 v103, 0xffff0000, v13
	v_pk_add_f32 v[170:171], v[170:171], v[172:173]
	v_pk_fma_f32 v[172:173], v[130:131], v[130:131], v[86:87] op_sel_hi:[1,1,0]
	v_mul_f32_e32 v86, v133, v133
	v_mul_f32_e32 v73, v102, v102
	v_mul_f32_e32 v75, v103, v103
	v_pk_fma_f32 v[188:189], v[132:133], v[132:133], v[86:87] op_sel_hi:[1,1,0]
	v_mov_b32_e32 v173, v73
	v_mov_b32_e32 v189, v75
	v_pk_add_f32 v[172:173], v[172:173], v[188:189]
	v_pk_mul_f32 v[146:147], v[92:93], v[146:147] op_sel_hi:[0,1]
	v_pk_add_f32 v[170:171], v[170:171], v[172:173]
	v_mov_b32_e32 v173, v168
	v_mov_b32_e32 v172, v170
	v_mov_b32_e32 v168, v171
	v_pk_add_f32 v[168:169], v[172:173], v[168:169]
	ds_bpermute_b32 v171, v162, v169
	ds_bpermute_b32 v170, v162, v168
	v_mov_b32_e32 v75, v137
	global_load_dwordx4 v[12:15], v[68:69], off nt
	v_mov_b32_e32 v86, v89
	v_mov_b32_e32 v104, v107
	s_waitcnt lgkmcnt(0)
	v_pk_add_f32 v[168:169], v[168:169], v[170:171]
	ds_bpermute_b32 v171, v163, v169
	ds_bpermute_b32 v170, v163, v168
	s_waitcnt lgkmcnt(0)
	v_pk_add_f32 v[168:169], v[168:169], v[170:171]
	ds_bpermute_b32 v171, v164, v169
	ds_bpermute_b32 v170, v164, v168
	s_waitcnt lgkmcnt(0)
	v_pk_add_f32 v[168:169], v[168:169], v[170:171]
	ds_bpermute_b32 v171, v165, v169
	ds_bpermute_b32 v170, v165, v168
	s_waitcnt lgkmcnt(0)
	v_pk_add_f32 v[168:169], v[168:169], v[170:171]
	ds_bpermute_b32 v171, v166, v169
	ds_bpermute_b32 v170, v166, v168
	s_waitcnt lgkmcnt(0)
	v_pk_add_f32 v[168:169], v[168:169], v[170:171]
	ds_bpermute_b32 v171, v167, v169
	ds_bpermute_b32 v170, v167, v168
	s_waitcnt lgkmcnt(0)
	v_pk_add_f32 v[168:169], v[168:169], v[170:171]
	s_nop 0
	v_pk_fma_f32 v[144:145], v[168:169], s[82:83], v[144:145] op_sel_hi:[1,0,0]
	global_load_dwordx4 v[168:171], v[66:67], off
	v_mul_f32_e32 v65, 0x4b800000, v145
	v_cmp_gt_f32_e64 s[4:5], s81, v145
	v_cmp_gt_f32_e32 vcc, s81, v144
	s_waitcnt vmcnt(0)
	v_pk_mul_f32 v[146:147], v[146:147], v[168:169]
	v_cndmask_b32_e64 v65, v145, v65, s[4:5]
	v_rsq_f32_e32 v65, v65
	v_pk_mul_f32 v[148:149], v[148:149], v[170:171]
	v_mul_f32_e32 v73, 0x45800000, v65
	v_cndmask_b32_e64 v100, v65, v73, s[4:5]
	v_mul_f32_e32 v65, 0x4b800000, v144
	v_cndmask_b32_e32 v65, v144, v65, vcc
	v_rsq_f32_e32 v65, v65
	s_nop 0
	v_mul_f32_e32 v73, 0x45800000, v65
	v_cndmask_b32_e32 v94, v65, v73, vcc
	v_add_u32_e32 v65, 0xffffe000, v64
	v_lshrrev_b32_e32 v65, 12, v65
	v_mad_u32_u24 v65, v65, s83, s83
	v_cmp_lt_i32_e32 vcc, s60, v64
	v_mov_b32_e32 v73, v137
	v_add_u32_e32 v64, s68, v64
	v_cndmask_b32_e32 v136, 0, v65, vcc
	v_lshl_add_u64 v[144:145], v[136:137], 2, s[84:85]
	v_lshl_add_u64 v[144:145], v[144:145], 0, s[62:63]
	v_lshl_add_u64 v[172:173], v[144:145], 0, v[72:73]
	global_load_dwordx4 v[188:191], v[172:173], off
	v_cmp_lt_i32_e32 vcc, s2, v64
	s_or_b64 s[8:9], vcc, s[8:9]
	s_waitcnt vmcnt(0)
	v_pk_fma_f32 v[50:51], v[190:191], v[148:149], v[50:51]
	v_pk_fma_f32 v[48:49], v[188:189], v[146:147], v[48:49]
	global_store_dwordx4 v[80:81], v[48:51], off offset:-3072
	s_nop 1
	v_pk_mul_f32 v[48:49], v[88:89], v[152:153] op_sel_hi:[0,1]
	v_pk_mul_f32 v[50:51], v[88:89], v[150:151] op_sel_hi:[0,1]
	v_pk_mul_f32 v[146:147], v[50:51], v[168:169]
	v_pk_mul_f32 v[48:49], v[48:49], v[170:171]
	s_nop 0
	v_pk_fma_f32 v[50:51], v[190:191], v[48:49], v[54:55]
	v_pk_fma_f32 v[48:49], v[188:189], v[146:147], v[52:53]
	global_store_dwordx4 v[82:83], v[48:51], off offset:-3072
	s_nop 1
	v_pk_mul_f32 v[48:49], v[100:101], v[156:157] op_sel_hi:[0,1]
	v_pk_mul_f32 v[50:51], v[100:101], v[154:155] op_sel_hi:[0,1]
	v_pk_mul_f32 v[52:53], v[168:169], v[50:51]
	v_pk_mul_f32 v[48:49], v[170:171], v[48:49]
	s_nop 0
	v_pk_fma_f32 v[50:51], v[190:191], v[48:49], v[58:59]
	v_pk_fma_f32 v[48:49], v[188:189], v[52:53], v[56:57]
	global_store_dwordx4 v[108:109], v[48:51], off offset:-3072
	v_mov_b32_e32 v56, v118
	v_mov_b32_e32 v57, v120
	v_pk_mul_f32 v[48:49], v[94:95], v[160:161] op_sel_hi:[0,1]
	v_pk_mul_f32 v[50:51], v[94:95], v[158:159] op_sel_hi:[0,1]
	v_pk_mul_f32 v[52:53], v[168:169], v[50:51]
	v_pk_mul_f32 v[48:49], v[170:171], v[48:49]
	v_mov_b32_e32 v120, v119
	v_pk_fma_f32 v[50:51], v[190:191], v[48:49], v[62:63]
	v_pk_fma_f32 v[48:49], v[188:189], v[52:53], v[60:61]
	global_store_dwordx4 v[68:69], v[48:51], off offset:-3072
	global_load_dwordx4 v[48:51], v[66:67], off offset:1024
	v_lshl_add_u64 v[52:53], v[144:145], 0, v[74:75]
	global_load_dwordx4 v[52:55], v[52:53], off
	v_pk_mul_f32 v[56:57], v[92:93], v[56:57] op_sel_hi:[0,1]
	v_pk_mul_f32 v[58:59], v[92:93], v[120:121] op_sel_hi:[0,1]
	s_waitcnt vmcnt(1)
	v_pk_mul_f32 v[58:59], v[58:59], v[50:51]
	v_pk_mul_f32 v[56:57], v[56:57], v[48:49]
	s_waitcnt vmcnt(0)
	v_pk_fma_f32 v[34:35], v[54:55], v[58:59], v[34:35]
	v_pk_fma_f32 v[32:33], v[52:53], v[56:57], v[32:33]
	global_store_dwordx4 v[80:81], v[32:35], off offset:-2048
	s_nop 1
	v_mov_b32_e32 v32, v122
	v_mov_b32_e32 v33, v124
	v_mov_b32_e32 v124, v123
	v_pk_mul_f32 v[32:33], v[88:89], v[32:33] op_sel_hi:[0,1]
	v_pk_mul_f32 v[34:35], v[88:89], v[124:125] op_sel_hi:[0,1]
	v_pk_mul_f32 v[34:35], v[34:35], v[50:51]
	v_pk_mul_f32 v[32:33], v[32:33], v[48:49]
	v_pk_fma_f32 v[34:35], v[54:55], v[34:35], v[38:39]
	v_pk_fma_f32 v[32:33], v[52:53], v[32:33], v[36:37]
	global_store_dwordx4 v[82:83], v[32:35], off offset:-2048
	v_lshl_add_u64 v[36:37], v[144:145], 0, v[76:77]
	s_nop 0
	v_mov_b32_e32 v32, v134
	v_mov_b32_e32 v33, v138
	v_mov_b32_e32 v138, v135
	v_pk_mul_f32 v[32:33], v[100:101], v[32:33] op_sel_hi:[0,1]
	v_pk_mul_f32 v[34:35], v[100:101], v[138:139] op_sel_hi:[0,1]
	v_pk_mul_f32 v[34:35], v[34:35], v[50:51]
	v_pk_mul_f32 v[32:33], v[32:33], v[48:49]
	v_pk_fma_f32 v[34:35], v[54:55], v[34:35], v[42:43]
	v_pk_fma_f32 v[32:33], v[52:53], v[32:33], v[40:41]
	global_store_dwordx4 v[108:109], v[32:35], off offset:-2048
	v_pk_mul_f32 v[40:41], v[92:93], v[110:111] op_sel_hi:[0,1]
	v_pk_mul_f32 v[42:43], v[92:93], v[112:113] op_sel_hi:[0,1]
	v_mov_b32_e32 v32, v140
	v_mov_b32_e32 v33, v142
	v_mov_b32_e32 v142, v141
	v_pk_mul_f32 v[32:33], v[94:95], v[32:33] op_sel_hi:[0,1]
	v_pk_mul_f32 v[34:35], v[94:95], v[142:143] op_sel_hi:[0,1]
	v_pk_mul_f32 v[34:35], v[50:51], v[34:35]
	v_pk_mul_f32 v[32:33], v[48:49], v[32:33]
	v_pk_fma_f32 v[34:35], v[54:55], v[34:35], v[46:47]
	v_pk_fma_f32 v[32:33], v[52:53], v[32:33], v[44:45]
	global_store_dwordx4 v[68:69], v[32:35], off offset:-2048
	global_load_dwordx4 v[32:35], v[66:67], off offset:2048
	s_waitcnt vmcnt(0)
	v_pk_mul_f32 v[42:43], v[42:43], v[34:35]
	global_load_dwordx4 v[36:39], v[36:37], off
	v_pk_mul_f32 v[40:41], v[40:41], v[32:33]
	s_waitcnt vmcnt(0)
	v_pk_fma_f32 v[18:19], v[38:39], v[42:43], v[18:19]
	v_pk_fma_f32 v[16:17], v[36:37], v[40:41], v[16:17]
	global_store_dwordx4 v[80:81], v[16:19], off offset:-1024
	s_nop 1
	v_pk_mul_f32 v[16:17], v[88:89], v[114:115] op_sel_hi:[0,1]
	v_pk_mul_f32 v[18:19], v[88:89], v[116:117] op_sel_hi:[0,1]
	v_pk_mul_f32 v[18:19], v[18:19], v[34:35]
	v_pk_mul_f32 v[16:17], v[16:17], v[32:33]
	v_pk_fma_f32 v[18:19], v[38:39], v[18:19], v[22:23]
	v_pk_fma_f32 v[16:17], v[36:37], v[16:17], v[20:21]
	global_store_dwordx4 v[82:83], v[16:19], off offset:-1024
	v_lshl_add_u64 v[20:21], v[144:145], 0, v[78:79]
	s_nop 0
	v_pk_mul_f32 v[16:17], v[100:101], v[126:127] op_sel_hi:[0,1]
	v_pk_mul_f32 v[18:19], v[100:101], v[128:129] op_sel_hi:[0,1]
	v_pk_mul_f32 v[18:19], v[18:19], v[34:35]
	v_pk_mul_f32 v[16:17], v[16:17], v[32:33]
	v_pk_fma_f32 v[18:19], v[38:39], v[18:19], v[26:27]
	v_pk_fma_f32 v[16:17], v[36:37], v[16:17], v[24:25]
	global_store_dwordx4 v[108:109], v[16:19], off offset:-1024
	v_pk_mul_f32 v[24:25], v[92:93], v[86:87] op_sel_hi:[0,1]
	v_pk_mul_f32 v[26:27], v[92:93], v[84:85] op_sel_hi:[0,1]
	v_pk_mul_f32 v[16:17], v[94:95], v[130:131] op_sel_hi:[0,1]
	v_pk_mul_f32 v[18:19], v[94:95], v[132:133] op_sel_hi:[0,1]
	v_pk_mul_f32 v[18:19], v[18:19], v[34:35]
	v_pk_mul_f32 v[16:17], v[16:17], v[32:33]
	v_pk_fma_f32 v[18:19], v[38:39], v[18:19], v[30:31]
	v_pk_fma_f32 v[16:17], v[36:37], v[16:17], v[28:29]
	global_store_dwordx4 v[68:69], v[16:19], off offset:-1024
	global_load_dwordx4 v[16:19], v[66:67], off offset:3072
	v_mov_b32_e32 v92, v95
	global_load_dwordx4 v[20:23], v[20:21], off
	s_waitcnt vmcnt(1)
	v_pk_mul_f32 v[26:27], v[26:27], v[18:19]
	v_pk_mul_f32 v[24:25], v[24:25], v[16:17]
	s_waitcnt vmcnt(0)
	v_pk_fma_f32 v[2:3], v[22:23], v[26:27], v[2:3]
	v_pk_fma_f32 v[0:1], v[20:21], v[24:25], v[0:1]
	global_store_dwordx4 v[80:81], v[0:3], off
	s_nop 1
	v_pk_mul_f32 v[0:1], v[88:89], v[92:93] op_sel_hi:[0,1]
	v_pk_mul_f32 v[2:3], v[88:89], v[90:91] op_sel_hi:[0,1]
	v_pk_mul_f32 v[2:3], v[2:3], v[18:19]
	v_pk_mul_f32 v[0:1], v[0:1], v[16:17]
	v_pk_fma_f32 v[2:3], v[22:23], v[2:3], v[6:7]
	v_pk_fma_f32 v[0:1], v[20:21], v[0:1], v[4:5]
	global_store_dwordx4 v[82:83], v[0:3], off
	s_nop 1
	v_pk_mul_f32 v[0:1], v[100:101], v[98:99] op_sel_hi:[0,1]
	v_pk_mul_f32 v[2:3], v[100:101], v[96:97] op_sel_hi:[0,1]
	v_pk_mul_f32 v[2:3], v[2:3], v[18:19]
	v_pk_mul_f32 v[0:1], v[0:1], v[16:17]
	v_pk_fma_f32 v[2:3], v[22:23], v[2:3], v[10:11]
	v_pk_fma_f32 v[0:1], v[20:21], v[0:1], v[8:9]
	global_store_dwordx4 v[68:69], v[0:3], off offset:-4096
	s_nop 1
	v_pk_mul_f32 v[0:1], v[94:95], v[104:105] op_sel_hi:[0,1]
	v_pk_mul_f32 v[2:3], v[94:95], v[102:103] op_sel_hi:[0,1]
	v_pk_mul_f32 v[2:3], v[2:3], v[18:19]
	v_pk_mul_f32 v[0:1], v[0:1], v[16:17]
	v_pk_fma_f32 v[2:3], v[22:23], v[2:3], v[14:15]
	v_pk_fma_f32 v[0:1], v[20:21], v[0:1], v[12:13]
	global_store_dwordx4 v[68:69], v[0:3], off
	v_lshl_add_u64 v[68:69], v[68:69], 0, s[72:73]
	s_andn2_b64 exec, exec, s[8:9]
	s_cbranch_execnz .LBB0_1512

.LBB0_1522:
	v_add_co_u32_e32 v4, vcc, 0xfefff000, v70
	s_mov_b32 s2, 0xff000000
	s_nop 0
	v_addc_co_u32_e32 v5, vcc, -1, v71, vcc
	v_add_co_u32_e32 v20, vcc, s33, v70
	global_load_dwordx2 v[6:7], v[4:5], off offset:-3584 nt
	global_load_dwordx4 v[48:51], v[72:73], off offset:-3072 nt
	global_load_dwordx2 v[12:13], v[4:5], off offset:-3072 nt
	global_load_dwordx4 v[16:19], v[72:73], off offset:-2048 nt
	global_load_dwordx2 v[14:15], v[4:5], off offset:-2560 nt
	global_load_dwordx4 v[8:11], v[72:73], off offset:-1024 nt
	global_load_dwordx2 v[22:23], v[4:5], off offset:-2048 nt
	global_load_dwordx4 v[0:3], v[72:73], off nt
	v_addc_co_u32_e32 v21, vcc, -1, v71, vcc
	global_load_dwordx2 v[24:25], v[20:21], off offset:-3584 nt
	v_mov_b32_e32 v77, v137
	v_mov_b32_e32 v79, v137
	v_mov_b32_e32 v81, v137
	s_waitcnt vmcnt(8)
	v_lshlrev_b32_e32 v26, 16, v6
	v_and_b32_e32 v27, 0xffff0000, v6
	v_lshlrev_b32_e32 v6, 16, v7
	v_and_b32_e32 v7, 0xffff0000, v7
	s_waitcnt vmcnt(0)
	v_lshlrev_b32_e32 v28, 16, v24
	v_and_b32_e32 v29, 0xffff0000, v24
	v_lshlrev_b32_e32 v24, 16, v25
	v_and_b32_e32 v25, 0xffff0000, v25
	v_pk_add_f32 v[150:151], v[6:7], v[24:25]
	global_load_dwordx2 v[6:7], v[20:21], off offset:-3072 nt
	v_pk_add_f32 v[148:149], v[26:27], v[28:29]
	v_lshlrev_b32_e32 v24, 16, v12
	v_and_b32_e32 v25, 0xffff0000, v12
	v_lshlrev_b32_e32 v12, 16, v13
	v_and_b32_e32 v13, 0xffff0000, v13
	s_waitcnt vmcnt(0)
	v_lshlrev_b32_e32 v26, 16, v6
	v_and_b32_e32 v27, 0xffff0000, v6
	v_lshlrev_b32_e32 v6, 16, v7
	v_and_b32_e32 v7, 0xffff0000, v7
	v_pk_add_f32 v[104:105], v[12:13], v[6:7]
	global_load_dwordx2 v[6:7], v[20:21], off offset:-2560 nt
	v_pk_add_f32 v[102:103], v[24:25], v[26:27]
	v_lshlrev_b32_e32 v12, 16, v14
	v_and_b32_e32 v13, 0xffff0000, v14
	v_mov_b32_e32 v168, v103
	v_mov_b32_e32 v169, v105
	v_pk_mul_f32 v[168:169], v[168:169], v[168:169]
	s_waitcnt vmcnt(0)
	v_lshlrev_b32_e32 v24, 16, v6
	v_and_b32_e32 v25, 0xffff0000, v6
	v_pk_add_f32 v[92:93], v[12:13], v[24:25]
	v_lshlrev_b32_e32 v12, 16, v15
	v_and_b32_e32 v13, 0xffff0000, v15
	v_lshlrev_b32_e32 v6, 16, v7
	v_and_b32_e32 v7, 0xffff0000, v7
	v_pk_add_f32 v[94:95], v[12:13], v[6:7]
	global_load_dwordx2 v[6:7], v[20:21], off offset:-2048 nt
	v_lshlrev_b32_e32 v12, 16, v22
	v_and_b32_e32 v13, 0xffff0000, v22
	v_mul_f32_e32 v136, v93, v93
	s_waitcnt vmcnt(0)
	v_lshlrev_b32_e32 v14, 16, v6
	v_and_b32_e32 v15, 0xffff0000, v6
	v_pk_add_f32 v[82:83], v[12:13], v[14:15]
	v_lshlrev_b32_e32 v12, 16, v23
	v_and_b32_e32 v13, 0xffff0000, v23
	v_lshlrev_b32_e32 v6, 16, v7
	v_and_b32_e32 v7, 0xffff0000, v7
	v_pk_add_f32 v[84:85], v[12:13], v[6:7]
	v_add_u32_e32 v6, 0x4001, v64
	v_ashrrev_i32_e32 v7, 31, v6
	v_lshlrev_b64 v[6:7], 12, v[6:7]
	v_lshl_add_u64 v[86:87], v[68:69], 0, v[6:7]
	global_load_dwordx2 v[22:23], v[4:5], off offset:-1536 nt
	global_load_dwordx4 v[52:55], v[86:87], off nt
	global_load_dwordx2 v[28:29], v[4:5], off offset:-1024 nt
	global_load_dwordx4 v[24:27], v[86:87], off offset:1024 nt
	global_load_dwordx2 v[30:31], v[4:5], off offset:-512 nt
	global_load_dwordx4 v[12:15], v[86:87], off offset:2048 nt
	global_load_dwordx2 v[32:33], v[4:5], off nt
	s_nop 0
	global_load_dwordx4 v[4:7], v[86:87], off offset:3072 nt
	global_load_dwordx2 v[34:35], v[20:21], off offset:-1536 nt
	v_pk_mul_f32 v[172:173], v[82:83], v[82:83]
	v_pk_mul_f32 v[188:189], v[84:85], v[84:85]
	s_waitcnt vmcnt(8)
	v_lshlrev_b32_e32 v36, 16, v22
	v_and_b32_e32 v37, 0xffff0000, v22
	v_lshlrev_b32_e32 v22, 16, v23
	v_and_b32_e32 v23, 0xffff0000, v23
	s_waitcnt vmcnt(0)
	v_lshlrev_b32_e32 v38, 16, v34
	v_and_b32_e32 v39, 0xffff0000, v34
	v_lshlrev_b32_e32 v34, 16, v35
	v_and_b32_e32 v35, 0xffff0000, v35
	v_pk_add_f32 v[154:155], v[22:23], v[34:35]
	global_load_dwordx2 v[22:23], v[20:21], off offset:-1024 nt
	v_pk_add_f32 v[152:153], v[36:37], v[38:39]
	global_load_dwordx2 v[20:21], v[20:21], off offset:-512 nt
	v_lshlrev_b32_e32 v34, 16, v28
	v_and_b32_e32 v35, 0xffff0000, v28
	v_lshlrev_b32_e32 v28, 16, v29
	v_and_b32_e32 v29, 0xffff0000, v29
	s_waitcnt vmcnt(1)
	v_lshlrev_b32_e32 v36, 16, v22
	v_and_b32_e32 v37, 0xffff0000, v22
	v_lshlrev_b32_e32 v22, 16, v23
	v_and_b32_e32 v23, 0xffff0000, v23
	v_pk_add_f32 v[114:115], v[28:29], v[22:23]
	v_lshlrev_b32_e32 v22, 16, v30
	v_and_b32_e32 v23, 0xffff0000, v30
	s_waitcnt vmcnt(0)
	v_lshlrev_b32_e32 v28, 16, v20
	v_and_b32_e32 v29, 0xffff0000, v20
	v_pk_add_f32 v[98:99], v[22:23], v[28:29]
	v_lshlrev_b32_e32 v22, 16, v31
	v_and_b32_e32 v23, 0xffff0000, v31
	v_lshlrev_b32_e32 v20, 16, v21
	v_and_b32_e32 v21, 0xffff0000, v21
	v_pk_add_f32 v[100:101], v[22:23], v[20:21]
	global_load_dwordx2 v[20:21], v[70:71], off offset:-4096 nt
	v_lshlrev_b32_e32 v22, 16, v32
	v_and_b32_e32 v23, 0xffff0000, v32
	v_add_co_u32_e32 v32, vcc, s2, v70
	v_pk_add_f32 v[112:113], v[34:35], v[36:37]
	s_movk_i32 s2, 0xdfff
	s_waitcnt vmcnt(0)
	v_lshlrev_b32_e32 v28, 16, v20
	v_and_b32_e32 v29, 0xffff0000, v20
	v_pk_add_f32 v[88:89], v[22:23], v[28:29]
	v_lshlrev_b32_e32 v22, 16, v33
	v_and_b32_e32 v23, 0xffff0000, v33
	v_lshlrev_b32_e32 v20, 16, v21
	v_and_b32_e32 v21, 0xffff0000, v21
	v_pk_add_f32 v[90:91], v[22:23], v[20:21]
	v_add_u32_e32 v20, 0x4002, v64
	v_ashrrev_i32_e32 v21, 31, v20
	v_lshlrev_b64 v[20:21], 12, v[20:21]
	v_addc_co_u32_e32 v33, vcc, -1, v71, vcc
	v_lshl_add_u64 v[96:97], v[68:69], 0, v[20:21]
	global_load_dwordx2 v[34:35], v[32:33], off offset:-3584 nt
	global_load_dwordx4 v[56:59], v[96:97], off nt
	global_load_dwordx2 v[40:41], v[32:33], off offset:-3072 nt
	global_load_dwordx4 v[36:39], v[96:97], off offset:1024 nt
	global_load_dwordx2 v[42:43], v[32:33], off offset:-2560 nt
	global_load_dwordx4 v[28:31], v[96:97], off offset:2048 nt
	global_load_dwordx2 v[44:45], v[32:33], off offset:-2048 nt
	global_load_dwordx4 v[20:23], v[96:97], off offset:3072 nt
	global_load_dwordx2 v[46:47], v[70:71], off offset:-3584 nt
	v_pk_mul_f32 v[190:191], v[90:91], v[90:91]
	s_waitcnt vmcnt(8)
	v_lshlrev_b32_e32 v60, 16, v34
	v_and_b32_e32 v61, 0xffff0000, v34
	v_lshlrev_b32_e32 v34, 16, v35
	v_and_b32_e32 v35, 0xffff0000, v35
	s_waitcnt vmcnt(0)
	v_lshlrev_b32_e32 v62, 16, v46
	v_and_b32_e32 v63, 0xffff0000, v46
	v_lshlrev_b32_e32 v46, 16, v47
	v_and_b32_e32 v47, 0xffff0000, v47
	v_pk_add_f32 v[158:159], v[34:35], v[46:47]
	global_load_dwordx2 v[34:35], v[70:71], off offset:-3072 nt
	v_pk_add_f32 v[156:157], v[60:61], v[62:63]
	v_lshlrev_b32_e32 v46, 16, v40
	v_and_b32_e32 v47, 0xffff0000, v40
	v_lshlrev_b32_e32 v40, 16, v41
	v_and_b32_e32 v41, 0xffff0000, v41
	s_waitcnt vmcnt(0)
	v_lshlrev_b32_e32 v60, 16, v34
	v_and_b32_e32 v61, 0xffff0000, v34
	v_lshlrev_b32_e32 v34, 16, v35
	v_and_b32_e32 v35, 0xffff0000, v35
	v_pk_add_f32 v[126:127], v[40:41], v[34:35]
	global_load_dwordx2 v[34:35], v[70:71], off offset:-2560 nt
	v_pk_add_f32 v[124:125], v[46:47], v[60:61]
	v_lshlrev_b32_e32 v40, 16, v42
	v_and_b32_e32 v41, 0xffff0000, v42
	s_waitcnt vmcnt(0)
	v_lshlrev_b32_e32 v46, 16, v34
	v_and_b32_e32 v47, 0xffff0000, v34
	v_pk_add_f32 v[116:117], v[40:41], v[46:47]
	v_lshlrev_b32_e32 v40, 16, v43
	v_and_b32_e32 v41, 0xffff0000, v43
	v_lshlrev_b32_e32 v34, 16, v35
	v_and_b32_e32 v35, 0xffff0000, v35
	v_pk_add_f32 v[118:119], v[40:41], v[34:35]
	global_load_dwordx2 v[34:35], v[70:71], off offset:-2048 nt
	v_lshlrev_b32_e32 v40, 16, v44
	v_and_b32_e32 v41, 0xffff0000, v44
	s_waitcnt vmcnt(0)
	v_lshlrev_b32_e32 v42, 16, v34
	v_and_b32_e32 v43, 0xffff0000, v34
	v_pk_add_f32 v[106:107], v[40:41], v[42:43]
	v_lshlrev_b32_e32 v40, 16, v45
	v_and_b32_e32 v41, 0xffff0000, v45
	v_lshlrev_b32_e32 v34, 16, v35
	v_and_b32_e32 v35, 0xffff0000, v35
	v_pk_add_f32 v[108:109], v[40:41], v[34:35]
	v_add_u32_e32 v34, 0x4003, v64
	v_ashrrev_i32_e32 v35, 31, v34
	v_lshlrev_b64 v[34:35], 12, v[34:35]
	v_lshl_add_u64 v[110:111], v[68:69], 0, v[34:35]
	global_load_dwordx2 v[120:121], v[32:33], off offset:-1536 nt
	global_load_dwordx4 v[60:63], v[110:111], off nt
	global_load_dwordx2 v[122:123], v[32:33], off offset:-1024 nt
	global_load_dwordx4 v[44:47], v[110:111], off offset:1024 nt
	global_load_dwordx2 v[130:131], v[32:33], off offset:-512 nt
	global_load_dwordx4 v[40:43], v[110:111], off offset:2048 nt
	global_load_dwordx2 v[138:139], v[32:33], off nt
	s_nop 0
	global_load_dwordx4 v[32:35], v[110:111], off offset:3072 nt
	global_load_dwordx2 v[128:129], v[70:71], off offset:-1536 nt
	v_pk_mul_f32 v[192:193], v[108:109], v[108:109]
	s_waitcnt vmcnt(8)
	v_lshlrev_b32_e32 v132, 16, v120
	v_and_b32_e32 v133, 0xffff0000, v120
	v_lshlrev_b32_e32 v120, 16, v121
	v_and_b32_e32 v121, 0xffff0000, v121
	s_waitcnt vmcnt(0)
	v_lshlrev_b32_e32 v134, 16, v128
	v_and_b32_e32 v135, 0xffff0000, v128
	v_lshlrev_b32_e32 v128, 16, v129
	v_and_b32_e32 v129, 0xffff0000, v129
	v_pk_add_f32 v[162:163], v[120:121], v[128:129]
	global_load_dwordx2 v[120:121], v[70:71], off offset:-1024 nt
	v_pk_add_f32 v[160:161], v[132:133], v[134:135]
	v_lshlrev_b32_e32 v128, 16, v122
	v_and_b32_e32 v129, 0xffff0000, v122
	v_lshlrev_b32_e32 v122, 16, v123
	v_and_b32_e32 v123, 0xffff0000, v123
	s_waitcnt vmcnt(0)
	v_lshlrev_b32_e32 v132, 16, v120
	v_and_b32_e32 v133, 0xffff0000, v120
	v_lshlrev_b32_e32 v120, 16, v121
	v_and_b32_e32 v121, 0xffff0000, v121
	v_pk_add_f32 v[134:135], v[122:123], v[120:121]
	global_load_dwordx2 v[120:121], v[70:71], off offset:-512 nt
	v_pk_add_f32 v[132:133], v[128:129], v[132:133]
	v_lshlrev_b32_e32 v122, 16, v130
	v_and_b32_e32 v123, 0xffff0000, v130
	s_waitcnt vmcnt(0)
	v_lshlrev_b32_e32 v128, 16, v120
	v_and_b32_e32 v129, 0xffff0000, v120
	v_pk_add_f32 v[128:129], v[122:123], v[128:129]
	v_lshlrev_b32_e32 v122, 16, v131
	v_and_b32_e32 v123, 0xffff0000, v131
	v_lshlrev_b32_e32 v120, 16, v121
	v_and_b32_e32 v121, 0xffff0000, v121
	v_pk_add_f32 v[130:131], v[122:123], v[120:121]
	global_load_dwordx2 v[122:123], v[70:71], off nt
	v_lshlrev_b32_e32 v120, 16, v138
	v_and_b32_e32 v121, 0xffff0000, v138
	v_lshlrev_b32_e32 v138, 16, v139
	v_and_b32_e32 v139, 0xffff0000, v139
	v_lshl_add_u64 v[70:71], v[70:71], 0, s[76:77]
	s_waitcnt vmcnt(0)
	v_lshlrev_b32_e32 v146, 16, v122
	v_and_b32_e32 v147, 0xffff0000, v122
	v_pk_add_f32 v[120:121], v[120:121], v[146:147]
	v_lshlrev_b32_e32 v122, 16, v123
	v_and_b32_e32 v123, 0xffff0000, v123
	v_mov_b32_e32 v146, v149
	v_mov_b32_e32 v147, v151
	v_pk_add_f32 v[122:123], v[138:139], v[122:123]
	v_mov_b32_e32 v138, v148
	v_mov_b32_e32 v139, v150
	v_pk_mul_f32 v[146:147], v[146:147], v[146:147]
	v_pk_mul_f32 v[194:195], v[122:123], v[122:123]
	v_pk_fma_f32 v[138:139], v[138:139], v[138:139], v[146:147]
	v_mov_b32_e32 v146, v102
	v_mov_b32_e32 v147, v104
	v_pk_fma_f32 v[146:147], v[146:147], v[146:147], v[168:169]
	v_pk_fma_f32 v[168:169], v[92:93], v[92:93], v[136:137] op_sel_hi:[1,1,0]
	v_mul_f32_e32 v136, v95, v95
	v_pk_add_f32 v[138:139], v[138:139], v[138:139] op_sel:[0,1] op_sel_hi:[1,0]
	v_pk_add_f32 v[146:147], v[146:147], v[146:147] op_sel:[0,1] op_sel_hi:[1,0]
	v_pk_fma_f32 v[170:171], v[94:95], v[94:95], v[136:137] op_sel_hi:[1,1,0]
	v_mov_b32_e32 v139, v172
	v_mov_b32_e32 v147, v173
	v_mov_b32_e32 v169, v188
	v_mov_b32_e32 v171, v189
	v_pk_add_f32 v[138:139], v[138:139], v[146:147]
	v_pk_add_f32 v[146:147], v[168:169], v[170:171]
	v_mov_b32_e32 v168, v153
	v_mov_b32_e32 v169, v155
	v_pk_add_f32 v[138:139], v[138:139], v[146:147]
	v_mov_b32_e32 v146, v152
	v_mov_b32_e32 v147, v154
	v_pk_mul_f32 v[168:169], v[168:169], v[168:169]
	v_mov_b32_e32 v170, v113
	v_mov_b32_e32 v171, v115
	v_pk_fma_f32 v[146:147], v[146:147], v[146:147], v[168:169]
	v_mov_b32_e32 v168, v112
	v_mov_b32_e32 v169, v114
	v_pk_mul_f32 v[170:171], v[170:171], v[170:171]
	v_mul_f32_e32 v136, v99, v99
	v_pk_fma_f32 v[168:169], v[168:169], v[168:169], v[170:171]
	v_pk_fma_f32 v[170:171], v[98:99], v[98:99], v[136:137] op_sel_hi:[1,1,0]
	v_mul_f32_e32 v136, v101, v101
	v_pk_add_f32 v[146:147], v[146:147], v[146:147] op_sel:[0,1] op_sel_hi:[1,0]
	v_pk_add_f32 v[168:169], v[168:169], v[168:169] op_sel:[0,1] op_sel_hi:[1,0]
	v_pk_fma_f32 v[172:173], v[100:101], v[100:101], v[136:137] op_sel_hi:[1,1,0]
	v_pk_mul_f32 v[188:189], v[88:89], v[88:89]
	v_mov_b32_e32 v171, v190
	v_mov_b32_e32 v147, v188
	v_mov_b32_e32 v169, v189
	v_mov_b32_e32 v173, v191
	v_pk_add_f32 v[146:147], v[146:147], v[168:169]
	v_pk_add_f32 v[168:169], v[170:171], v[172:173]
	v_mov_b32_e32 v170, v157
	v_pk_add_f32 v[146:147], v[146:147], v[168:169]
	v_mov_b32_e32 v169, v138
	v_mov_b32_e32 v168, v146
	v_mov_b32_e32 v138, v147
	v_mov_b32_e32 v171, v159
	v_pk_add_f32 v[138:139], v[168:169], v[138:139]
	v_mov_b32_e32 v168, v156
	v_mov_b32_e32 v169, v158
	v_pk_mul_f32 v[170:171], v[170:171], v[170:171]
	v_mov_b32_e32 v172, v125
	v_mov_b32_e32 v173, v127
	ds_bpermute_b32 v147, v141, v139
	ds_bpermute_b32 v146, v141, v138
	v_pk_fma_f32 v[168:169], v[168:169], v[168:169], v[170:171]
	v_mov_b32_e32 v170, v124
	v_mov_b32_e32 v171, v126
	v_pk_mul_f32 v[172:173], v[172:173], v[172:173]
	v_mul_f32_e32 v136, v117, v117
	v_pk_fma_f32 v[170:171], v[170:171], v[170:171], v[172:173]
	v_pk_fma_f32 v[172:173], v[116:117], v[116:117], v[136:137] op_sel_hi:[1,1,0]
	v_mul_f32_e32 v136, v119, v119
	v_pk_add_f32 v[168:169], v[168:169], v[168:169] op_sel:[0,1] op_sel_hi:[1,0]
	v_pk_add_f32 v[170:171], v[170:171], v[170:171] op_sel:[0,1] op_sel_hi:[1,0]
	v_pk_fma_f32 v[188:189], v[118:119], v[118:119], v[136:137] op_sel_hi:[1,1,0]
	v_pk_mul_f32 v[190:191], v[106:107], v[106:107]
	v_mov_b32_e32 v173, v192
	v_mov_b32_e32 v169, v190
	v_mov_b32_e32 v171, v191
	v_mov_b32_e32 v189, v193
	v_pk_add_f32 v[168:169], v[168:169], v[170:171]
	v_pk_add_f32 v[170:171], v[172:173], v[188:189]
	v_mov_b32_e32 v172, v161
	v_mov_b32_e32 v173, v163
	s_waitcnt lgkmcnt(0)
	v_pk_add_f32 v[138:139], v[138:139], v[146:147]
	v_pk_add_f32 v[168:169], v[168:169], v[170:171]
	v_mov_b32_e32 v170, v160
	v_mov_b32_e32 v171, v162
	v_pk_mul_f32 v[172:173], v[172:173], v[172:173]
	v_mov_b32_e32 v188, v133
	v_mov_b32_e32 v189, v135
	ds_bpermute_b32 v147, v143, v139
	ds_bpermute_b32 v146, v143, v138
	v_pk_fma_f32 v[170:171], v[170:171], v[170:171], v[172:173]
	v_mov_b32_e32 v172, v132
	v_mov_b32_e32 v173, v134
	v_pk_mul_f32 v[188:189], v[188:189], v[188:189]
	v_mul_f32_e32 v136, v129, v129
	v_pk_fma_f32 v[172:173], v[172:173], v[172:173], v[188:189]
	v_pk_fma_f32 v[188:189], v[128:129], v[128:129], v[136:137] op_sel_hi:[1,1,0]
	v_mul_f32_e32 v136, v131, v131
	v_pk_add_f32 v[170:171], v[170:171], v[170:171] op_sel:[0,1] op_sel_hi:[1,0]
	v_pk_add_f32 v[172:173], v[172:173], v[172:173] op_sel:[0,1] op_sel_hi:[1,0]
	v_pk_fma_f32 v[190:191], v[130:131], v[130:131], v[136:137] op_sel_hi:[1,1,0]
	v_pk_mul_f32 v[192:193], v[120:121], v[120:121]
	v_mov_b32_e32 v189, v194
	v_mov_b32_e32 v171, v192
	v_mov_b32_e32 v173, v193
	v_mov_b32_e32 v191, v195
	v_pk_add_f32 v[170:171], v[170:171], v[172:173]
	v_pk_add_f32 v[172:173], v[188:189], v[190:191]
	s_waitcnt lgkmcnt(0)
	v_pk_add_f32 v[138:139], v[138:139], v[146:147]
	v_pk_add_f32 v[170:171], v[170:171], v[172:173]
	ds_bpermute_b32 v147, v145, v139
	ds_bpermute_b32 v146, v145, v138
	v_mov_b32_e32 v172, v170
	v_mov_b32_e32 v173, v168
	v_mov_b32_e32 v168, v171
	v_pk_add_f32 v[168:169], v[172:173], v[168:169]
	ds_bpermute_b32 v171, v141, v169
	ds_bpermute_b32 v170, v141, v168
	s_waitcnt lgkmcnt(2)
	v_pk_add_f32 v[138:139], v[138:139], v[146:147]
	ds_bpermute_b32 v147, v164, v139
	ds_bpermute_b32 v146, v164, v138
	s_waitcnt lgkmcnt(2)
	v_pk_add_f32 v[168:169], v[168:169], v[170:171]
	ds_bpermute_b32 v171, v143, v169
	ds_bpermute_b32 v170, v143, v168
	s_waitcnt lgkmcnt(2)
	v_pk_add_f32 v[138:139], v[138:139], v[146:147]
	ds_bpermute_b32 v147, v165, v139
	ds_bpermute_b32 v146, v165, v138
	s_waitcnt lgkmcnt(2)
	v_pk_add_f32 v[168:169], v[168:169], v[170:171]
	ds_bpermute_b32 v171, v145, v169
	ds_bpermute_b32 v170, v145, v168
	s_waitcnt lgkmcnt(2)
	v_pk_add_f32 v[138:139], v[138:139], v[146:147]
	ds_bpermute_b32 v147, v166, v139
	ds_bpermute_b32 v146, v166, v138
	s_waitcnt lgkmcnt(2)
	v_pk_add_f32 v[168:169], v[168:169], v[170:171]
	ds_bpermute_b32 v171, v164, v169
	ds_bpermute_b32 v170, v164, v168
	s_waitcnt lgkmcnt(2)
	v_pk_add_f32 v[138:139], v[138:139], v[146:147]
	v_mov_b64_e32 v[146:147], s[90:91]
	v_pk_fma_f32 v[138:139], v[138:139], s[82:83], v[146:147] op_sel_hi:[1,0,0]
	s_waitcnt lgkmcnt(0)
	v_pk_add_f32 v[168:169], v[168:169], v[170:171]
	v_mul_f32_e32 v65, 0x4b800000, v139
	v_cmp_gt_f32_e64 s[4:5], s81, v139
	ds_bpermute_b32 v171, v165, v169
	ds_bpermute_b32 v170, v165, v168
	v_cndmask_b32_e64 v65, v139, v65, s[4:5]
	v_rsq_f32_e32 v65, v65
	v_cmp_gt_f32_e32 vcc, s81, v138
	s_waitcnt lgkmcnt(0)
	v_pk_add_f32 v[168:169], v[168:169], v[170:171]
	v_mul_f32_e32 v75, 0x45800000, v65
	v_cndmask_b32_e64 v140, v65, v75, s[4:5]
	v_mul_f32_e32 v65, 0x4b800000, v138
	ds_bpermute_b32 v171, v166, v169
	ds_bpermute_b32 v170, v166, v168
	v_cndmask_b32_e32 v65, v138, v65, vcc
	v_rsq_f32_e32 v65, v65
	v_pk_mul_f32 v[150:151], v[150:151], v[140:141] op_sel_hi:[1,0]
	v_pk_mul_f32 v[148:149], v[148:149], v[140:141] op_sel_hi:[1,0]
	s_waitcnt lgkmcnt(0)
	v_pk_add_f32 v[168:169], v[168:169], v[170:171]
	v_mul_f32_e32 v75, 0x45800000, v65
	v_pk_fma_f32 v[146:147], v[168:169], s[82:83], v[146:147] op_sel_hi:[1,0,0]
	v_cndmask_b32_e32 v138, v65, v75, vcc
	v_mul_f32_e32 v65, 0x4b800000, v147
	v_cmp_gt_f32_e64 s[4:5], s81, v147
	v_cmp_gt_f32_e32 vcc, s81, v146
	global_load_dwordx4 v[168:171], v[66:67], off
	v_cndmask_b32_e64 v65, v147, v65, s[4:5]
	v_rsq_f32_e32 v65, v65
	s_waitcnt vmcnt(0)
	v_pk_mul_f32 v[148:149], v[148:149], v[168:169]
	v_mul_f32_e32 v75, 0x45800000, v65
	v_cndmask_b32_e64 v144, v65, v75, s[4:5]
	v_mul_f32_e32 v65, 0x4b800000, v146
	v_cndmask_b32_e32 v65, v146, v65, vcc
	v_rsq_f32_e32 v65, v65
	v_pk_mul_f32 v[150:151], v[150:151], v[170:171]
	v_mul_f32_e32 v75, 0x45800000, v65
	v_cndmask_b32_e32 v142, v65, v75, vcc
	v_add_u32_e32 v65, 0x2000, v64
	v_lshrrev_b32_e32 v65, 12, v65
	v_mad_u32_u24 v65, v65, s83, s83
	v_cmp_lt_i32_e32 vcc, s2, v64
	v_mov_b32_e32 v75, v137
	v_add_u32_e32 v64, s68, v64
	v_cndmask_b32_e32 v136, 0, v65, vcc
	v_lshl_add_u64 v[146:147], v[136:137], 2, s[84:85]
	v_lshl_add_u64 v[146:147], v[146:147], 0, s[62:63]
	v_lshl_add_u64 v[172:173], v[146:147], 0, v[74:75]
	global_load_dwordx4 v[188:191], v[172:173], off
	v_cmp_lt_i32_e32 vcc, s60, v64
	s_or_b64 s[8:9], vcc, s[8:9]
	s_waitcnt vmcnt(0)
	v_pk_fma_f32 v[50:51], v[190:191], v[150:151], v[50:51]
	v_pk_fma_f32 v[48:49], v[188:189], v[148:149], v[48:49]
	global_store_dwordx4 v[72:73], v[48:51], off offset:-3072
	s_nop 1
	v_pk_mul_f32 v[48:49], v[154:155], v[138:139] op_sel_hi:[1,0]
	v_pk_mul_f32 v[50:51], v[152:153], v[138:139] op_sel_hi:[1,0]
	v_pk_mul_f32 v[48:49], v[48:49], v[170:171]
	v_pk_mul_f32 v[148:149], v[50:51], v[168:169]
	v_pk_fma_f32 v[50:51], v[190:191], v[48:49], v[54:55]
	v_pk_fma_f32 v[48:49], v[188:189], v[148:149], v[52:53]
	global_store_dwordx4 v[86:87], v[48:51], off
	s_nop 1
	v_pk_mul_f32 v[48:49], v[158:159], v[144:145] op_sel_hi:[1,0]
	v_pk_mul_f32 v[50:51], v[156:157], v[144:145] op_sel_hi:[1,0]
	v_pk_mul_f32 v[48:49], v[170:171], v[48:49]
	v_pk_mul_f32 v[52:53], v[168:169], v[50:51]
	v_pk_fma_f32 v[50:51], v[190:191], v[48:49], v[58:59]
	v_pk_fma_f32 v[48:49], v[188:189], v[52:53], v[56:57]
	global_store_dwordx4 v[96:97], v[48:51], off
	v_pk_mul_f32 v[56:57], v[102:103], v[140:141] op_sel_hi:[1,0]
	v_pk_mul_f32 v[58:59], v[104:105], v[140:141] op_sel_hi:[1,0]
	v_pk_mul_f32 v[48:49], v[162:163], v[142:143] op_sel_hi:[1,0]
	v_pk_mul_f32 v[50:51], v[160:161], v[142:143] op_sel_hi:[1,0]
	v_pk_mul_f32 v[48:49], v[170:171], v[48:49]
	v_pk_mul_f32 v[52:53], v[168:169], v[50:51]
	v_pk_fma_f32 v[50:51], v[190:191], v[48:49], v[62:63]
	v_pk_fma_f32 v[48:49], v[188:189], v[52:53], v[60:61]
	global_store_dwordx4 v[110:111], v[48:51], off
	global_load_dwordx4 v[48:51], v[66:67], off offset:1024
	v_lshl_add_u64 v[52:53], v[146:147], 0, v[76:77]
	global_load_dwordx4 v[52:55], v[52:53], off
	s_waitcnt vmcnt(1)
	v_pk_mul_f32 v[58:59], v[58:59], v[50:51]
	v_pk_mul_f32 v[56:57], v[56:57], v[48:49]
	s_waitcnt vmcnt(0)
	v_pk_fma_f32 v[18:19], v[54:55], v[58:59], v[18:19]
	v_pk_fma_f32 v[16:17], v[52:53], v[56:57], v[16:17]
	global_store_dwordx4 v[72:73], v[16:19], off offset:-2048
	s_nop 1
	v_pk_mul_f32 v[16:17], v[112:113], v[138:139] op_sel_hi:[1,0]
	v_pk_mul_f32 v[18:19], v[114:115], v[138:139] op_sel_hi:[1,0]
	v_pk_mul_f32 v[16:17], v[16:17], v[48:49]
	v_pk_mul_f32 v[18:19], v[18:19], v[50:51]
	v_pk_fma_f32 v[16:17], v[52:53], v[16:17], v[24:25]
	v_pk_fma_f32 v[18:19], v[54:55], v[18:19], v[26:27]
	global_store_dwordx4 v[86:87], v[16:19], off offset:1024
	v_lshl_add_u64 v[24:25], v[146:147], 0, v[78:79]
	s_nop 0
	v_pk_mul_f32 v[16:17], v[124:125], v[144:145] op_sel_hi:[1,0]
	v_pk_mul_f32 v[18:19], v[126:127], v[144:145] op_sel_hi:[1,0]
	v_pk_mul_f32 v[16:17], v[16:17], v[48:49]
	v_pk_mul_f32 v[18:19], v[18:19], v[50:51]
	v_pk_fma_f32 v[16:17], v[52:53], v[16:17], v[36:37]
	v_pk_fma_f32 v[18:19], v[54:55], v[18:19], v[38:39]
	global_store_dwordx4 v[96:97], v[16:19], off offset:1024
	v_pk_mul_f32 v[36:37], v[92:93], v[140:141] op_sel_hi:[1,0]
	v_pk_mul_f32 v[38:39], v[94:95], v[140:141] op_sel_hi:[1,0]
	v_pk_mul_f32 v[16:17], v[132:133], v[142:143] op_sel_hi:[1,0]
	v_pk_mul_f32 v[18:19], v[134:135], v[142:143] op_sel_hi:[1,0]
	v_pk_mul_f32 v[16:17], v[48:49], v[16:17]
	v_pk_mul_f32 v[18:19], v[50:51], v[18:19]
	v_pk_fma_f32 v[16:17], v[52:53], v[16:17], v[44:45]
	v_pk_fma_f32 v[18:19], v[54:55], v[18:19], v[46:47]
	global_store_dwordx4 v[110:111], v[16:19], off offset:1024
	global_load_dwordx4 v[16:19], v[66:67], off offset:2048
	s_waitcnt vmcnt(0)
	v_pk_mul_f32 v[38:39], v[38:39], v[18:19]
	global_load_dwordx4 v[24:27], v[24:25], off
	v_pk_mul_f32 v[36:37], v[36:37], v[16:17]
	s_waitcnt vmcnt(0)
	v_pk_fma_f32 v[10:11], v[26:27], v[38:39], v[10:11]
	v_pk_fma_f32 v[8:9], v[24:25], v[36:37], v[8:9]
	global_store_dwordx4 v[72:73], v[8:11], off offset:-1024
	s_nop 1
	v_pk_mul_f32 v[8:9], v[98:99], v[138:139] op_sel_hi:[1,0]
	v_pk_mul_f32 v[10:11], v[100:101], v[138:139] op_sel_hi:[1,0]
	v_pk_mul_f32 v[8:9], v[8:9], v[16:17]
	v_pk_mul_f32 v[10:11], v[10:11], v[18:19]
	v_pk_fma_f32 v[8:9], v[24:25], v[8:9], v[12:13]
	v_pk_fma_f32 v[10:11], v[26:27], v[10:11], v[14:15]
	global_store_dwordx4 v[86:87], v[8:11], off offset:2048
	v_lshl_add_u64 v[12:13], v[146:147], 0, v[80:81]
	s_nop 0
	v_pk_mul_f32 v[8:9], v[116:117], v[144:145] op_sel_hi:[1,0]
	v_pk_mul_f32 v[10:11], v[118:119], v[144:145] op_sel_hi:[1,0]
	v_pk_mul_f32 v[8:9], v[8:9], v[16:17]
	v_pk_mul_f32 v[10:11], v[10:11], v[18:19]
	v_pk_fma_f32 v[8:9], v[24:25], v[8:9], v[28:29]
	v_pk_fma_f32 v[10:11], v[26:27], v[10:11], v[30:31]
	global_store_dwordx4 v[96:97], v[8:11], off offset:2048
	s_nop 1
	v_pk_mul_f32 v[8:9], v[128:129], v[142:143] op_sel_hi:[1,0]
	v_pk_mul_f32 v[10:11], v[130:131], v[142:143] op_sel_hi:[1,0]
	v_pk_mul_f32 v[8:9], v[8:9], v[16:17]
	v_pk_mul_f32 v[10:11], v[10:11], v[18:19]
	v_pk_fma_f32 v[8:9], v[24:25], v[8:9], v[40:41]
	v_pk_fma_f32 v[10:11], v[26:27], v[10:11], v[42:43]
	global_store_dwordx4 v[110:111], v[8:11], off offset:2048
	global_load_dwordx4 v[8:11], v[66:67], off offset:3072
	v_pk_mul_f32 v[16:17], v[82:83], v[140:141] op_sel_hi:[1,0]
	global_load_dwordx4 v[12:15], v[12:13], off
	v_pk_mul_f32 v[18:19], v[84:85], v[140:141] op_sel_hi:[1,0]
	s_waitcnt vmcnt(1)
	v_pk_mul_f32 v[16:17], v[16:17], v[8:9]
	v_pk_mul_f32 v[18:19], v[18:19], v[10:11]
	s_waitcnt vmcnt(0)
	v_pk_fma_f32 v[0:1], v[12:13], v[16:17], v[0:1]
	v_pk_fma_f32 v[2:3], v[14:15], v[18:19], v[2:3]
	global_store_dwordx4 v[72:73], v[0:3], off
	v_lshl_add_u64 v[72:73], v[72:73], 0, s[72:73]
	s_nop 0
	v_pk_mul_f32 v[0:1], v[88:89], v[138:139] op_sel_hi:[1,0]
	v_pk_mul_f32 v[2:3], v[90:91], v[138:139] op_sel_hi:[1,0]
	v_pk_mul_f32 v[0:1], v[0:1], v[8:9]
	v_pk_mul_f32 v[2:3], v[2:3], v[10:11]
	v_pk_fma_f32 v[0:1], v[12:13], v[0:1], v[4:5]
	v_pk_fma_f32 v[2:3], v[14:15], v[2:3], v[6:7]
	global_store_dwordx4 v[86:87], v[0:3], off offset:3072
	s_nop 1
	v_pk_mul_f32 v[0:1], v[106:107], v[144:145] op_sel_hi:[1,0]
	v_pk_mul_f32 v[2:3], v[108:109], v[144:145] op_sel_hi:[1,0]
	v_pk_mul_f32 v[0:1], v[0:1], v[8:9]
	v_pk_mul_f32 v[2:3], v[2:3], v[10:11]
	v_pk_fma_f32 v[0:1], v[12:13], v[0:1], v[20:21]
	v_pk_fma_f32 v[2:3], v[14:15], v[2:3], v[22:23]
	global_store_dwordx4 v[96:97], v[0:3], off offset:3072
	s_nop 1
	v_pk_mul_f32 v[0:1], v[120:121], v[142:143] op_sel_hi:[1,0]
	v_pk_mul_f32 v[2:3], v[122:123], v[142:143] op_sel_hi:[1,0]
	v_pk_mul_f32 v[0:1], v[0:1], v[8:9]
	v_pk_mul_f32 v[2:3], v[2:3], v[10:11]
	v_pk_fma_f32 v[0:1], v[12:13], v[0:1], v[32:33]
	v_pk_fma_f32 v[2:3], v[14:15], v[2:3], v[34:35]
	global_store_dwordx4 v[110:111], v[0:3], off offset:3072
	s_andn2_b64 exec, exec, s[8:9]
	s_cbranch_execnz .LBB0_1522

.LBB0_1534:
	v_cmp_gt_i32_e32 vcc, s12, v76
	v_add_u32_e32 v72, 0xffffdfff, v82
	v_lshl_add_u64 v[0:1], v[82:83], 0, -1
	v_cndmask_b32_e32 v1, 0, v1, vcc
	v_cndmask_b32_e32 v0, v72, v0, vcc
	v_mov_b32_e32 v22, s19
	v_mov_b32_e32 v23, s17
	v_mov_b32_e32 v48, s18
	v_mov_b32_e32 v49, s16
	v_cndmask_b32_e32 v3, v22, v23, vcc
	v_cndmask_b32_e32 v2, v48, v49, vcc
	v_lshlrev_b64 v[0:1], 12, v[0:1]
	s_mov_b32 s2, 0xfb9ff000
	v_lshl_add_u64 v[0:1], v[2:3], 0, v[0:1]
	v_add_co_u32_e64 v4, s[4:5], s2, v86
	v_lshl_add_u64 v[0:1], v[0:1], 0, v[136:137]
	s_nop 0
	v_addc_co_u32_e64 v5, s[4:5], -1, v87, s[4:5]
	global_load_dwordx4 v[40:43], v[0:1], off nt
	global_load_dwordx2 v[122:123], v[4:5], off offset:-3584 nt
	global_load_dwordx4 v[28:31], v[0:1], off offset:1024 nt
	global_load_dwordx2 v[120:121], v[4:5], off offset:-3072 nt
	global_load_dwordx4 v[12:15], v[0:1], off offset:2048 nt
	global_load_dwordx2 v[118:119], v[4:5], off offset:-2560 nt
	s_nop 0
	global_load_dwordx4 v[0:3], v[0:1], off offset:3072 nt
	s_nop 0
	global_load_dwordx2 v[6:7], v[4:5], off offset:-2048 nt
	v_cmp_gt_i32_e64 s[4:5], s12, v82
	s_mov_b32 s2, 0xfba00000
	v_add_u32_e32 v10, 0xffffe001, v82
	v_cndmask_b32_e64 v9, v22, v23, s[4:5]
	v_cndmask_b32_e64 v8, v48, v49, s[4:5]
	v_add_u32_e32 v50, 0xffffe002, v82
	v_mov_b32_e32 v93, v137
	v_mov_b32_e32 v95, v137
	v_add_u32_e32 v76, s68, v76
	s_waitcnt vmcnt(6)
	v_and_b32_e32 v149, 0xffff0000, v123
	v_and_b32_e32 v147, 0xffff0000, v122
	v_lshlrev_b32_e32 v148, 16, v123
	v_mul_f32_e32 v74, v149, v149
	s_waitcnt vmcnt(4)
	v_and_b32_e32 v129, 0xffff0000, v121
	v_and_b32_e32 v128, 0xffff0000, v120
	s_waitcnt vmcnt(0)
	v_lshlrev_b32_e32 v75, 16, v6
	v_and_b32_e32 v73, 0xffff0000, v6
	v_add_u32_e32 v6, 0xffffe000, v82
	v_lshlrev_b32_e32 v96, 16, v7
	v_and_b32_e32 v97, 0xffff0000, v7
	v_cndmask_b32_e64 v7, 0, v83, s[4:5]
	v_cndmask_b32_e64 v6, v6, v82, s[4:5]
	v_lshlrev_b64 v[6:7], 12, v[6:7]
	v_lshl_add_u64 v[6:7], v[8:9], 0, v[6:7]
	v_add_co_u32_e64 v110, s[4:5], s2, v86
	v_lshl_add_u64 v[6:7], v[6:7], 0, v[136:137]
	s_nop 0
	v_addc_co_u32_e64 v111, s[4:5], -1, v87, s[4:5]
	global_load_dwordx4 v[44:47], v[6:7], off nt
	global_load_dwordx2 v[124:125], v[4:5], off offset:-1536 nt
	global_load_dwordx4 v[32:35], v[6:7], off offset:1024 nt
	global_load_dwordx2 v[116:117], v[4:5], off offset:-1024 nt
	global_load_dwordx4 v[16:19], v[6:7], off offset:2048 nt
	global_load_dwordx2 v[70:71], v[4:5], off offset:-512 nt
	s_nop 0
	global_load_dwordx4 v[4:7], v[6:7], off offset:3072 nt
	v_lshlrev_b32_e32 v146, 16, v122
	global_load_dwordx2 v[8:9], v[110:111], off offset:-4096 nt
	v_pk_fma_f32 v[126:127], v[148:149], v[148:149], v[74:75] op_sel_hi:[1,1,0]
	v_lshlrev_b32_e32 v131, 16, v121
	v_lshlrev_b32_e32 v130, 16, v120
	v_pk_mul_f32 v[120:121], v[128:129], v[128:129]
	v_mul_f32_e32 v74, v147, v147
	v_pk_fma_f32 v[132:133], v[130:131], v[130:131], v[120:121]
	v_lshlrev_b32_e32 v120, 16, v118
	v_and_b32_e32 v121, 0xffff0000, v118
	v_lshlrev_b32_e32 v122, 16, v119
	v_and_b32_e32 v123, 0xffff0000, v119
	v_pk_fma_f32 v[118:119], v[146:147], v[146:147], v[74:75] op_sel_hi:[1,1,0]
	v_mov_b32_e32 v134, v126
	v_mov_b32_e32 v74, v118
	v_mov_b32_e32 v135, v75
	v_pk_add_f32 v[118:119], v[118:119], v[126:127]
	v_pk_mul_f32 v[126:127], v[74:75], v[134:135]
	v_mul_f32_e32 v77, v73, v73
	v_mov_b32_e32 v119, v127
	v_pk_add_f32 v[126:127], v[132:133], v[132:133] op_sel:[0,1] op_sel_hi:[1,0]
	v_mul_f32_e32 v74, v121, v121
	v_mov_b32_e32 v127, v77
	v_pk_add_f32 v[118:119], v[118:119], v[126:127]
	v_pk_fma_f32 v[126:127], v[120:121], v[120:121], v[74:75] op_sel_hi:[1,1,0]
	v_mul_f32_e32 v74, v123, v123
	v_mul_f32_e32 v89, v96, v96
	v_mul_f32_e32 v91, v97, v97
	v_pk_fma_f32 v[132:133], v[122:123], v[122:123], v[74:75] op_sel_hi:[1,1,0]
	v_mov_b32_e32 v127, v89
	v_mov_b32_e32 v133, v91
	v_pk_add_f32 v[126:127], v[126:127], v[132:133]
	s_mov_b64 s[2:3], 0x2000
	v_pk_add_f32 v[118:119], v[118:119], v[126:127]
	s_waitcnt vmcnt(6)
	v_and_b32_e32 v151, 0xffff0000, v124
	v_and_b32_e32 v153, 0xffff0000, v125
	v_lshlrev_b32_e32 v150, 16, v124
	v_lshlrev_b32_e32 v152, 16, v125
	v_mul_f32_e32 v74, v153, v153
	s_waitcnt vmcnt(4)
	v_and_b32_e32 v133, 0xffff0000, v117
	v_and_b32_e32 v132, 0xffff0000, v116
	s_waitcnt vmcnt(0)
	v_lshlrev_b32_e32 v101, 16, v8
	v_and_b32_e32 v99, 0xffff0000, v8
	v_lshlrev_b32_e32 v102, 16, v9
	v_and_b32_e32 v103, 0xffff0000, v9
	v_lshl_add_u64 v[8:9], v[82:83], 0, 1
	v_cmp_gt_i32_e64 s[4:5], s12, v8
	v_lshlrev_b32_e32 v124, 16, v70
	v_and_b32_e32 v125, 0xffff0000, v70
	v_cndmask_b32_e64 v9, 0, v9, s[4:5]
	v_cndmask_b32_e64 v8, v10, v8, s[4:5]
	v_cndmask_b32_e64 v11, v22, v23, s[4:5]
	v_cndmask_b32_e64 v10, v48, v49, s[4:5]
	v_lshlrev_b64 v[8:9], 12, v[8:9]
	v_lshl_add_u64 v[8:9], v[10:11], 0, v[8:9]
	v_lshl_add_u64 v[8:9], v[8:9], 0, v[136:137]
	global_load_dwordx4 v[52:55], v[8:9], off nt
	global_load_dwordx2 v[68:69], v[110:111], off offset:-3584 nt
	global_load_dwordx4 v[36:39], v[8:9], off offset:1024 nt
	global_load_dwordx2 v[66:67], v[110:111], off offset:-3072 nt
	global_load_dwordx4 v[24:27], v[8:9], off offset:2048 nt
	global_load_dwordx2 v[64:65], v[110:111], off offset:-2560 nt
	s_nop 0
	global_load_dwordx4 v[8:11], v[8:9], off offset:3072 nt
	s_nop 0
	global_load_dwordx2 v[20:21], v[110:111], off offset:-2048 nt
	v_mul_f32_e32 v70, v151, v151
	v_pk_fma_f32 v[138:139], v[152:153], v[152:153], v[74:75] op_sel_hi:[1,1,0]
	v_lshlrev_b32_e32 v135, 16, v117
	v_lshlrev_b32_e32 v134, 16, v116
	v_pk_mul_f32 v[116:117], v[132:133], v[132:133]
	v_lshlrev_b32_e32 v126, 16, v71
	v_and_b32_e32 v127, 0xffff0000, v71
	v_pk_fma_f32 v[70:71], v[150:151], v[150:151], v[70:71] op_sel_hi:[1,1,0]
	v_pk_fma_f32 v[116:117], v[134:135], v[134:135], v[116:117]
	v_mov_b32_e32 v100, v70
	v_mov_b32_e32 v140, v138
	v_mov_b32_e32 v141, v101
	v_mul_f32_e32 v74, v99, v99
	v_pk_add_f32 v[70:71], v[70:71], v[138:139]
	v_pk_mul_f32 v[138:139], v[100:101], v[140:141]
	v_pk_add_f32 v[116:117], v[116:117], v[116:117] op_sel:[0,1] op_sel_hi:[1,0]
	v_mov_b32_e32 v71, v139
	v_mov_b32_e32 v117, v74
	v_mul_f32_e32 v74, v125, v125
	v_pk_add_f32 v[70:71], v[70:71], v[116:117]
	v_pk_fma_f32 v[116:117], v[124:125], v[124:125], v[74:75] op_sel_hi:[1,1,0]
	v_mul_f32_e32 v74, v127, v127
	v_mul_f32_e32 v77, v102, v102
	v_mul_f32_e32 v89, v103, v103
	v_pk_fma_f32 v[138:139], v[126:127], v[126:127], v[74:75] op_sel_hi:[1,1,0]
	v_mov_b32_e32 v117, v77
	v_mov_b32_e32 v139, v89
	v_pk_add_f32 v[116:117], v[116:117], v[138:139]
	s_waitcnt vmcnt(6)
	v_and_b32_e32 v163, 0xffff0000, v68
	v_pk_add_f32 v[70:71], v[70:71], v[116:117]
	v_mov_b32_e32 v117, v118
	v_mov_b32_e32 v116, v70
	v_mov_b32_e32 v118, v71
	v_pk_add_f32 v[70:71], v[116:117], v[118:119]
	s_waitcnt vmcnt(0)
	v_lshlrev_b32_e32 v107, 16, v20
	v_and_b32_e32 v105, 0xffff0000, v20
	v_lshlrev_b32_e32 v108, 16, v21
	v_and_b32_e32 v109, 0xffff0000, v21
	v_lshl_add_u64 v[20:21], v[82:83], 0, 2
	v_cmp_gt_i32_e64 s[4:5], s12, v20
	ds_bpermute_b32 v117, v187, v71
	ds_bpermute_b32 v116, v187, v70
	v_cndmask_b32_e64 v21, 0, v21, s[4:5]
	v_cndmask_b32_e64 v20, v50, v20, s[4:5]
	v_cndmask_b32_e64 v23, v22, v23, s[4:5]
	v_cndmask_b32_e64 v22, v48, v49, s[4:5]
	v_lshlrev_b64 v[20:21], 12, v[20:21]
	v_lshl_add_u64 v[20:21], v[22:23], 0, v[20:21]
	v_lshl_add_u64 v[20:21], v[20:21], 0, v[136:137]
	global_load_dwordx4 v[56:59], v[20:21], off nt
	global_load_dwordx2 v[158:159], v[110:111], off offset:-1536 nt
	global_load_dwordx4 v[60:63], v[20:21], off offset:1024 nt
	global_load_dwordx2 v[142:143], v[110:111], off offset:-1024 nt
	global_load_dwordx4 v[48:51], v[20:21], off offset:2048 nt
	global_load_dwordx2 v[144:145], v[110:111], off offset:-512 nt
	s_nop 0
	global_load_dwordx4 v[20:23], v[20:21], off offset:3072 nt
	s_nop 0
	global_load_dwordx2 v[114:115], v[110:111], off nt
	s_waitcnt lgkmcnt(0)
	v_pk_add_f32 v[70:71], v[70:71], v[116:117]
	ds_bpermute_b32 v117, v188, v71
	ds_bpermute_b32 v116, v188, v70
	v_and_b32_e32 v165, 0xffff0000, v69
	v_lshlrev_b32_e32 v162, 16, v68
	v_lshlrev_b32_e32 v164, 16, v69
	v_mul_f32_e32 v68, v165, v165
	s_waitcnt lgkmcnt(0)
	v_pk_add_f32 v[70:71], v[70:71], v[116:117]
	ds_bpermute_b32 v117, v189, v71
	ds_bpermute_b32 v116, v189, v70
	v_and_b32_e32 v155, 0xffff0000, v67
	v_and_b32_e32 v154, 0xffff0000, v66
	v_lshlrev_b32_e32 v138, 16, v64
	v_and_b32_e32 v139, 0xffff0000, v64
	s_waitcnt lgkmcnt(0)
	v_pk_add_f32 v[70:71], v[70:71], v[116:117]
	ds_bpermute_b32 v117, v190, v71
	ds_bpermute_b32 v116, v190, v70
	v_mul_f32_e32 v64, v163, v163
	v_pk_fma_f32 v[68:69], v[164:165], v[164:165], v[68:69] op_sel_hi:[1,1,0]
	v_lshlrev_b32_e32 v157, 16, v67
	v_lshlrev_b32_e32 v156, 16, v66
	s_waitcnt lgkmcnt(0)
	v_pk_add_f32 v[70:71], v[70:71], v[116:117]
	ds_bpermute_b32 v117, v191, v71
	ds_bpermute_b32 v116, v191, v70
	v_pk_mul_f32 v[66:67], v[154:155], v[154:155]
	v_lshlrev_b32_e32 v140, 16, v65
	v_and_b32_e32 v141, 0xffff0000, v65
	v_pk_fma_f32 v[64:65], v[162:163], v[162:163], v[64:65] op_sel_hi:[1,1,0]
	s_waitcnt lgkmcnt(0)
	v_pk_add_f32 v[70:71], v[70:71], v[116:117]
	ds_bpermute_b32 v117, v192, v71
	ds_bpermute_b32 v116, v192, v70
	v_pk_fma_f32 v[66:67], v[156:157], v[156:157], v[66:67]
	v_mov_b32_e32 v106, v64
	v_mul_f32_e32 v77, v105, v105
	v_pk_add_f32 v[64:65], v[64:65], v[68:69]
	s_waitcnt lgkmcnt(0)
	v_pk_add_f32 v[70:71], v[70:71], v[116:117]
	v_mov_b64_e32 v[116:117], s[90:91]
	v_pk_fma_f32 v[70:71], v[70:71], s[82:83], v[116:117] op_sel_hi:[1,0,0]
	v_pk_add_f32 v[66:67], v[66:67], v[66:67] op_sel:[0,1] op_sel_hi:[1,0]
	v_mul_f32_e32 v74, 0x4b800000, v71
	v_cmp_gt_f32_e64 s[6:7], s81, v71
	v_cmp_gt_f32_e64 s[4:5], s81, v70
	v_mov_b32_e32 v67, v77
	v_cndmask_b32_e64 v71, v71, v74, s[6:7]
	v_rsq_f32_e32 v71, v71
	v_mul_f32_e32 v89, v108, v108
	v_mul_f32_e32 v91, v109, v109
	v_lshl_add_u64 v[82:83], v[82:83], 0, s[68:69]
	v_mul_f32_e32 v74, 0x45800000, v71
	v_cndmask_b32_e64 v98, v71, v74, s[6:7]
	v_mul_f32_e32 v71, 0x4b800000, v70
	v_cndmask_b32_e64 v70, v70, v71, s[4:5]
	v_rsq_f32_e32 v70, v70
	v_pk_mul_f32 v[148:149], v[98:99], v[148:149] op_sel_hi:[0,1]
	v_pk_mul_f32 v[146:147], v[98:99], v[146:147] op_sel_hi:[0,1]
	v_pk_mul_f32 v[96:97], v[98:99], v[96:97] op_sel_hi:[0,1]
	v_mul_f32_e32 v71, 0x45800000, v70
	v_cndmask_b32_e64 v74, v70, v71, s[4:5]
	v_mov_b32_e32 v70, v68
	v_mov_b32_e32 v71, v107
	v_pk_mul_f32 v[68:69], v[106:107], v[70:71]
	v_pk_mul_f32 v[150:151], v[74:75], v[150:151] op_sel_hi:[0,1]
	v_mov_b32_e32 v65, v69
	v_pk_add_f32 v[64:65], v[64:65], v[66:67]
	v_mul_f32_e32 v66, v139, v139
	v_mul_f32_e32 v68, v141, v141
	v_pk_fma_f32 v[66:67], v[138:139], v[138:139], v[66:67] op_sel_hi:[1,1,0]
	v_pk_fma_f32 v[68:69], v[140:141], v[140:141], v[68:69] op_sel_hi:[1,1,0]
	v_mov_b32_e32 v67, v89
	v_mov_b32_e32 v69, v91
	v_pk_add_f32 v[66:67], v[66:67], v[68:69]
	s_waitcnt vmcnt(6)
	v_and_b32_e32 v167, 0xffff0000, v158
	v_and_b32_e32 v169, 0xffff0000, v159
	v_pk_add_f32 v[64:65], v[64:65], v[66:67]
	v_lshlrev_b32_e32 v166, 16, v158
	v_lshlrev_b32_e32 v168, 16, v159
	v_mul_f32_e32 v66, v169, v169
	s_waitcnt vmcnt(4)
	v_and_b32_e32 v159, 0xffff0000, v143
	v_and_b32_e32 v158, 0xffff0000, v142
	v_mul_f32_e32 v70, v167, v167
	s_waitcnt vmcnt(0)
	v_lshlrev_b32_e32 v113, 16, v114
	v_pk_fma_f32 v[66:67], v[168:169], v[168:169], v[66:67] op_sel_hi:[1,1,0]
	v_lshlrev_b32_e32 v161, 16, v143
	v_lshlrev_b32_e32 v160, 16, v142
	v_pk_mul_f32 v[68:69], v[158:159], v[158:159]
	v_pk_fma_f32 v[70:71], v[166:167], v[166:167], v[70:71] op_sel_hi:[1,1,0]
	v_and_b32_e32 v111, 0xffff0000, v114
	v_pk_fma_f32 v[68:69], v[160:161], v[160:161], v[68:69]
	v_mov_b32_e32 v112, v70
	v_mov_b32_e32 v118, v66
	v_mov_b32_e32 v119, v113
	v_mul_f32_e32 v77, v111, v111
	v_pk_add_f32 v[66:67], v[70:71], v[66:67]
	v_pk_mul_f32 v[70:71], v[112:113], v[118:119]
	v_pk_add_f32 v[68:69], v[68:69], v[68:69] op_sel:[0,1] op_sel_hi:[1,0]
	v_lshlrev_b32_e32 v142, 16, v144
	v_and_b32_e32 v143, 0xffff0000, v144
	v_lshlrev_b32_e32 v144, 16, v145
	v_and_b32_e32 v145, 0xffff0000, v145
	v_mov_b32_e32 v67, v71
	v_mov_b32_e32 v69, v77
	v_lshlrev_b32_e32 v114, 16, v115
	v_and_b32_e32 v115, 0xffff0000, v115
	v_pk_add_f32 v[66:67], v[66:67], v[68:69]
	v_mul_f32_e32 v68, v143, v143
	v_mul_f32_e32 v70, v145, v145
	v_mul_f32_e32 v89, v114, v114
	v_mul_f32_e32 v91, v115, v115
	v_pk_fma_f32 v[68:69], v[142:143], v[142:143], v[68:69] op_sel_hi:[1,1,0]
	v_pk_fma_f32 v[70:71], v[144:145], v[144:145], v[70:71] op_sel_hi:[1,1,0]
	v_mov_b32_e32 v69, v89
	v_mov_b32_e32 v71, v91
	v_pk_add_f32 v[68:69], v[68:69], v[70:71]
	v_mov_b32_e32 v89, v137
	v_pk_add_f32 v[66:67], v[66:67], v[68:69]
	v_mov_b32_e32 v69, v64
	v_mov_b32_e32 v68, v66
	v_mov_b32_e32 v64, v67
	v_pk_add_f32 v[64:65], v[68:69], v[64:65]
	ds_bpermute_b32 v67, v187, v65
	ds_bpermute_b32 v66, v187, v64
	v_mov_b32_e32 v91, v137
	v_mov_b32_e32 v110, v113
	s_waitcnt lgkmcnt(0)
	v_pk_add_f32 v[64:65], v[64:65], v[66:67]
	ds_bpermute_b32 v67, v188, v65
	ds_bpermute_b32 v66, v188, v64
	s_waitcnt lgkmcnt(0)
	v_pk_add_f32 v[64:65], v[64:65], v[66:67]
	ds_bpermute_b32 v67, v189, v65
	ds_bpermute_b32 v66, v189, v64
	s_waitcnt lgkmcnt(0)
	v_pk_add_f32 v[64:65], v[64:65], v[66:67]
	ds_bpermute_b32 v67, v190, v65
	ds_bpermute_b32 v66, v190, v64
	s_waitcnt lgkmcnt(0)
	v_pk_add_f32 v[64:65], v[64:65], v[66:67]
	ds_bpermute_b32 v67, v191, v65
	ds_bpermute_b32 v66, v191, v64
	s_waitcnt lgkmcnt(0)
	v_pk_add_f32 v[64:65], v[64:65], v[66:67]
	ds_bpermute_b32 v67, v192, v65
	ds_bpermute_b32 v66, v192, v64
	s_waitcnt lgkmcnt(0)
	v_pk_add_f32 v[64:65], v[64:65], v[66:67]
	s_nop 0
	v_pk_fma_f32 v[64:65], v[64:65], s[82:83], v[116:117] op_sel_hi:[1,0,0]
	s_nop 0
	v_mul_f32_e32 v66, 0x4b800000, v65
	v_cmp_gt_f32_e64 s[6:7], s81, v65
	v_cmp_gt_f32_e64 s[4:5], s81, v64
	s_nop 0
	v_cndmask_b32_e64 v65, v65, v66, s[6:7]
	v_rsq_f32_e32 v65, v65
	s_nop 0
	v_mul_f32_e32 v66, 0x45800000, v65
	v_cndmask_b32_e64 v106, v65, v66, s[6:7]
	v_mul_f32_e32 v65, 0x4b800000, v64
	v_cndmask_b32_e64 v64, v64, v65, s[4:5]
	v_rsq_f32_e32 v64, v64
	v_pk_mul_f32 v[162:163], v[106:107], v[162:163] op_sel_hi:[0,1]
	v_mul_f32_e32 v65, 0x45800000, v64
	v_cndmask_b32_e64 v100, v64, v65, s[4:5]
	v_lshrrev_b32_e32 v64, 12, v72
	v_mad_u32_u24 v64, v64, s83, s83
	v_cndmask_b32_e64 v64, v64, 0, vcc
	v_mov_b32_e32 v65, v137
	v_lshl_add_u64 v[118:119], v[64:65], 2, s[84:85]
	v_lshl_add_u64 v[170:171], v[118:119], 0, s[2:3]
	global_load_dwordx4 v[64:67], v[78:79], off
	v_lshl_add_u64 v[68:69], v[170:171], 0, v[88:89]
	global_load_dwordx4 v[68:71], v[68:69], off
	s_movk_i32 s2, 0xd000
	v_add_co_u32_e32 v172, vcc, s2, v84
	v_pk_mul_f32 v[166:167], v[100:101], v[166:167] op_sel_hi:[0,1]
	s_nop 0
	v_addc_co_u32_e32 v173, vcc, -1, v85, vcc
	v_mov_b32_e32 v72, v75
	v_pk_mul_f32 v[72:73], v[98:99], v[72:73] op_sel_hi:[0,1]
	s_mov_b64 s[2:3], 0x3000
	s_waitcnt vmcnt(1)
	v_pk_mul_f32 v[146:147], v[146:147], v[64:65]
	v_pk_mul_f32 v[148:149], v[148:149], v[66:67]
	s_waitcnt vmcnt(0)
	v_pk_fma_f32 v[40:41], v[68:69], v[146:147], v[40:41]
	v_pk_fma_f32 v[42:43], v[70:71], v[148:149], v[42:43]
	v_pk_mul_f32 v[148:149], v[40:41], v[40:41]
	v_pk_mul_f32 v[146:147], v[42:43], v[42:43]
	v_pk_mul_f32 v[150:151], v[150:151], v[64:65]
	v_pk_mov_b32 v[194:195], v[148:149], v[146:147] op_sel:[1,0]
	v_mov_b32_e32 v149, v147
	v_pk_add_f32 v[146:147], v[194:195], v[148:149]
	v_pk_mul_f32 v[148:149], v[74:75], v[152:153] op_sel_hi:[0,1]
	v_pk_mul_f32 v[148:149], v[148:149], v[66:67]
	v_pk_fma_f32 v[44:45], v[68:69], v[150:151], v[44:45]
	v_pk_fma_f32 v[46:47], v[70:71], v[148:149], v[46:47]
	v_pk_mul_f32 v[152:153], v[44:45], v[44:45]
	v_pk_mul_f32 v[150:151], v[46:47], v[46:47]
	v_pk_mul_f32 v[162:163], v[64:65], v[162:163]
	v_pk_mov_b32 v[194:195], v[152:153], v[150:151] op_sel:[1,0]
	v_mov_b32_e32 v153, v151
	v_pk_add_f32 v[150:151], v[194:195], v[152:153]
	v_pk_mul_f32 v[152:153], v[106:107], v[164:165] op_sel_hi:[0,1]
	v_pk_mul_f32 v[152:153], v[66:67], v[152:153]
	v_pk_fma_f32 v[52:53], v[68:69], v[162:163], v[52:53]
	v_pk_fma_f32 v[54:55], v[70:71], v[152:153], v[54:55]
	v_pk_mul_f32 v[162:163], v[52:53], v[52:53]
	v_pk_mul_f32 v[152:153], v[54:55], v[54:55]
	v_add_co_u32_e32 v148, vcc, s80, v84
	v_pk_mov_b32 v[194:195], v[162:163], v[152:153] op_sel:[1,0]
	v_mov_b32_e32 v163, v153
	v_pk_add_f32 v[152:153], v[194:195], v[162:163]
	v_pk_mul_f32 v[162:163], v[100:101], v[168:169] op_sel_hi:[0,1]
	v_addc_co_u32_e32 v149, vcc, -1, v85, vcc
	v_pk_mul_f32 v[64:65], v[64:65], v[166:167]
	v_pk_mul_f32 v[66:67], v[66:67], v[162:163]
	v_add_co_u32_e32 v164, vcc, s33, v84
	v_pk_fma_f32 v[58:59], v[70:71], v[66:67], v[58:59]
	v_pk_fma_f32 v[56:57], v[68:69], v[64:65], v[56:57]
	v_addc_co_u32_e32 v165, vcc, -1, v85, vcc
	v_pk_mul_f32 v[64:65], v[58:59], v[58:59]
	v_pk_mul_f32 v[66:67], v[56:57], v[56:57]
	global_store_dwordx4 v[172:173], v[40:43], off offset:-3072
	global_store_dwordx4 v[148:149], v[44:47], off offset:-3072
	global_store_dwordx4 v[164:165], v[52:55], off offset:-3072
	global_store_dwordx4 v[84:85], v[56:59], off offset:-3072
	v_pk_mov_b32 v[68:69], v[66:67], v[64:65] op_sel:[1,0]
	v_mov_b32_e32 v67, v65
	v_pk_add_f32 v[162:163], v[68:69], v[66:67]
	global_load_dwordx4 v[64:67], v[78:79], off offset:1024
	v_lshl_add_u64 v[68:69], v[170:171], 0, v[90:91]
	global_load_dwordx4 v[68:71], v[68:69], off
	v_mov_b32_e32 v166, v130
	v_mov_b32_e32 v167, v128
	v_mov_b32_e32 v128, v131
	v_pk_mul_f32 v[166:167], v[98:99], v[166:167] op_sel_hi:[0,1]
	v_pk_mul_f32 v[128:129], v[98:99], v[128:129] op_sel_hi:[0,1]
	s_waitcnt vmcnt(1)
	v_pk_mul_f32 v[128:129], v[128:129], v[66:67]
	v_pk_mul_f32 v[130:131], v[166:167], v[64:65]
	s_waitcnt vmcnt(0)
	v_pk_fma_f32 v[30:31], v[70:71], v[128:129], v[30:31]
	v_pk_fma_f32 v[28:29], v[68:69], v[130:131], v[28:29]
	v_pk_mul_f32 v[130:131], v[30:31], v[30:31]
	v_pk_mul_f32 v[128:129], v[28:29], v[28:29]
	global_store_dwordx4 v[172:173], v[28:31], off offset:-2048
	v_pk_mov_b32 v[166:167], v[128:129], v[130:131] op_sel:[1,0]
	v_mov_b32_e32 v129, v131
	v_mov_b32_e32 v130, v134
	v_mov_b32_e32 v131, v132
	v_mov_b32_e32 v132, v135
	v_pk_mul_f32 v[130:131], v[74:75], v[130:131] op_sel_hi:[0,1]
	v_pk_mul_f32 v[132:133], v[74:75], v[132:133] op_sel_hi:[0,1]
	v_pk_mul_f32 v[132:133], v[132:133], v[66:67]
	v_pk_mul_f32 v[130:131], v[130:131], v[64:65]
	v_pk_fma_f32 v[34:35], v[70:71], v[132:133], v[34:35]
	v_pk_fma_f32 v[32:33], v[68:69], v[130:131], v[32:33]
	v_pk_mul_f32 v[132:133], v[34:35], v[34:35]
	v_pk_mul_f32 v[130:131], v[32:33], v[32:33]
	global_store_dwordx4 v[148:149], v[32:35], off offset:-2048
	v_pk_mov_b32 v[134:135], v[130:131], v[132:133] op_sel:[1,0]
	v_mov_b32_e32 v131, v133
	v_mov_b32_e32 v132, v156
	v_mov_b32_e32 v133, v154
	v_mov_b32_e32 v154, v157
	v_pk_add_f32 v[130:131], v[134:135], v[130:131]
	v_pk_mul_f32 v[132:133], v[106:107], v[132:133] op_sel_hi:[0,1]
	v_pk_mul_f32 v[134:135], v[106:107], v[154:155] op_sel_hi:[0,1]
	v_pk_mul_f32 v[134:135], v[134:135], v[66:67]
	v_pk_mul_f32 v[132:133], v[132:133], v[64:65]
	v_pk_fma_f32 v[38:39], v[70:71], v[134:135], v[38:39]
	v_pk_fma_f32 v[36:37], v[68:69], v[132:133], v[36:37]
	v_pk_mul_f32 v[134:135], v[38:39], v[38:39]
	v_pk_mul_f32 v[132:133], v[36:37], v[36:37]
	global_store_dwordx4 v[164:165], v[36:39], off offset:-2048
	v_pk_mov_b32 v[154:155], v[132:133], v[134:135] op_sel:[1,0]
	v_mov_b32_e32 v133, v135
	v_mov_b32_e32 v134, v160
	v_mov_b32_e32 v135, v158
	v_mov_b32_e32 v158, v161
	v_pk_add_f32 v[132:133], v[154:155], v[132:133]
	v_pk_mul_f32 v[134:135], v[100:101], v[134:135] op_sel_hi:[0,1]
	v_pk_mul_f32 v[154:155], v[100:101], v[158:159] op_sel_hi:[0,1]
	v_pk_mul_f32 v[66:67], v[66:67], v[154:155]
	v_pk_mul_f32 v[64:65], v[64:65], v[134:135]
	v_pk_fma_f32 v[70:71], v[70:71], v[66:67], v[62:63]
	v_pk_fma_f32 v[68:69], v[68:69], v[64:65], v[60:61]
	v_pk_mul_f32 v[62:63], v[70:71], v[70:71]
	v_pk_mul_f32 v[60:61], v[68:69], v[68:69]
	global_store_dwordx4 v[84:85], v[68:71], off offset:-2048
	v_pk_mov_b32 v[64:65], v[60:61], v[62:63] op_sel:[1,0]
	v_mov_b32_e32 v61, v63
	v_pk_add_f32 v[134:135], v[64:65], v[60:61]
	global_load_dwordx4 v[154:157], v[78:79], off offset:2048
	v_lshl_add_u64 v[60:61], v[170:171], 0, v[92:93]
	global_load_dwordx4 v[158:161], v[60:61], off
	v_pk_mul_f32 v[60:61], v[98:99], v[120:121] op_sel_hi:[0,1]
	v_pk_mul_f32 v[62:63], v[98:99], v[122:123] op_sel_hi:[0,1]
	v_pk_add_f32 v[128:129], v[166:167], v[128:129]
	s_waitcnt vmcnt(1)
	v_pk_mul_f32 v[62:63], v[62:63], v[156:157]
	v_pk_mul_f32 v[60:61], v[60:61], v[154:155]
	s_waitcnt vmcnt(0)
	v_pk_fma_f32 v[66:67], v[160:161], v[62:63], v[14:15]
	v_pk_fma_f32 v[64:65], v[158:159], v[60:61], v[12:13]
	v_pk_mul_f32 v[12:13], v[74:75], v[124:125] op_sel_hi:[0,1]
	v_pk_mul_f32 v[14:15], v[74:75], v[126:127] op_sel_hi:[0,1]
	v_pk_mul_f32 v[14:15], v[14:15], v[156:157]
	v_pk_mul_f32 v[12:13], v[12:13], v[154:155]
	v_pk_fma_f32 v[62:63], v[160:161], v[14:15], v[18:19]
	v_pk_fma_f32 v[60:61], v[158:159], v[12:13], v[16:17]
	v_pk_mul_f32 v[12:13], v[106:107], v[138:139] op_sel_hi:[0,1]
	v_pk_mul_f32 v[14:15], v[106:107], v[140:141] op_sel_hi:[0,1]
	v_pk_mul_f32 v[14:15], v[14:15], v[156:157]
	v_pk_mul_f32 v[12:13], v[12:13], v[154:155]
	v_pk_fma_f32 v[18:19], v[160:161], v[14:15], v[26:27]
	v_pk_fma_f32 v[16:17], v[158:159], v[12:13], v[24:25]
	v_pk_mul_f32 v[12:13], v[100:101], v[142:143] op_sel_hi:[0,1]
	v_pk_mul_f32 v[14:15], v[100:101], v[144:145] op_sel_hi:[0,1]
	v_pk_mul_f32 v[14:15], v[14:15], v[156:157]
	v_pk_mul_f32 v[12:13], v[12:13], v[154:155]
	v_pk_fma_f32 v[14:15], v[160:161], v[14:15], v[50:51]
	v_pk_fma_f32 v[12:13], v[158:159], v[12:13], v[48:49]
	global_store_dwordx4 v[172:173], v[64:67], off offset:-1024
	global_store_dwordx4 v[148:149], v[60:63], off offset:-1024
	global_store_dwordx4 v[164:165], v[16:19], off offset:-1024
	global_store_dwordx4 v[84:85], v[12:15], off offset:-1024
	global_load_dwordx4 v[24:27], v[78:79], off offset:3072
	v_lshl_add_u64 v[48:49], v[170:171], 0, v[94:95]
	global_load_dwordx4 v[48:51], v[48:49], off
	s_waitcnt vmcnt(1)
	v_pk_mul_f32 v[72:73], v[72:73], v[24:25]
	v_pk_mul_f32 v[96:97], v[96:97], v[26:27]
	s_waitcnt vmcnt(0)
	v_pk_fma_f32 v[0:1], v[48:49], v[72:73], v[0:1]
	v_pk_fma_f32 v[2:3], v[50:51], v[96:97], v[2:3]
	v_mul_f32_e32 v75, v0, v0
	v_mul_f32_e32 v77, v1, v1
	v_pk_add_f32 v[72:73], v[146:147], v[146:147] op_sel:[0,1] op_sel_hi:[1,0]
	v_pk_add_f32 v[96:97], v[128:129], v[128:129] op_sel:[0,1] op_sel_hi:[1,0]
	v_mov_b32_e32 v73, v75
	v_mov_b32_e32 v97, v77
	v_pk_add_f32 v[72:73], v[72:73], v[96:97]
	v_mul_f32_e32 v96, v65, v65
	v_mul_f32_e32 v98, v2, v2
	v_pk_fma_f32 v[96:97], v[64:65], v[64:65], v[96:97] op_sel_hi:[1,1,0]
	v_mul_f32_e32 v104, v3, v3
	v_mov_b32_e32 v97, v98
	v_mul_f32_e32 v98, v67, v67
	v_pk_fma_f32 v[120:121], v[66:67], v[66:67], v[98:99] op_sel_hi:[1,1,0]
	v_mov_b32_e32 v98, v101
	v_mov_b32_e32 v121, v104
	v_pk_add_f32 v[96:97], v[96:97], v[120:121]
	v_mov_b32_e32 v104, v107
	v_pk_add_f32 v[72:73], v[72:73], v[96:97]
	v_pk_mul_f32 v[96:97], v[74:75], v[102:103] op_sel_hi:[0,1]
	v_pk_mul_f32 v[74:75], v[74:75], v[98:99] op_sel_hi:[0,1]
	v_pk_mul_f32 v[74:75], v[74:75], v[24:25]
	v_pk_mul_f32 v[96:97], v[96:97], v[26:27]
	v_pk_fma_f32 v[4:5], v[48:49], v[74:75], v[4:5]
	v_pk_fma_f32 v[6:7], v[50:51], v[96:97], v[6:7]
	v_mul_f32_e32 v77, v4, v4
	v_mul_f32_e32 v98, v5, v5
	v_pk_add_f32 v[74:75], v[150:151], v[150:151] op_sel:[0,1] op_sel_hi:[1,0]
	v_pk_add_f32 v[96:97], v[130:131], v[130:131] op_sel:[0,1] op_sel_hi:[1,0]
	v_mov_b32_e32 v75, v77
	v_mov_b32_e32 v97, v98
	v_pk_add_f32 v[74:75], v[74:75], v[96:97]
	v_mul_f32_e32 v96, v61, v61
	v_mul_f32_e32 v99, v6, v6
	v_pk_fma_f32 v[96:97], v[60:61], v[60:61], v[96:97] op_sel_hi:[1,1,0]
	v_mul_f32_e32 v98, v63, v63
	v_mul_f32_e32 v101, v7, v7
	v_mov_b32_e32 v97, v99
	v_pk_fma_f32 v[98:99], v[62:63], v[62:63], v[98:99] op_sel_hi:[1,1,0]
	global_store_dwordx4 v[148:149], v[0:3], off offset:-4096
	v_mov_b32_e32 v99, v101
	v_pk_add_f32 v[96:97], v[96:97], v[98:99]
	v_pk_mul_f32 v[98:99], v[106:107], v[104:105] op_sel_hi:[0,1]
	v_pk_add_f32 v[74:75], v[74:75], v[96:97]
	v_pk_mul_f32 v[96:97], v[106:107], v[108:109] op_sel_hi:[0,1]
	v_pk_mul_f32 v[98:99], v[98:99], v[24:25]
	v_pk_mul_f32 v[96:97], v[96:97], v[26:27]
	v_pk_fma_f32 v[8:9], v[48:49], v[98:99], v[8:9]
	v_pk_fma_f32 v[10:11], v[50:51], v[96:97], v[10:11]
	v_mul_f32_e32 v77, v8, v8
	v_mul_f32_e32 v101, v9, v9
	v_pk_add_f32 v[96:97], v[152:153], v[152:153] op_sel:[0,1] op_sel_hi:[1,0]
	v_pk_add_f32 v[98:99], v[132:133], v[132:133] op_sel:[0,1] op_sel_hi:[1,0]
	v_mov_b32_e32 v97, v77
	v_mov_b32_e32 v99, v101
	v_pk_add_f32 v[96:97], v[96:97], v[98:99]
	v_mul_f32_e32 v98, v17, v17
	v_mul_f32_e32 v102, v10, v10
	v_pk_fma_f32 v[98:99], v[16:17], v[16:17], v[98:99] op_sel_hi:[1,1,0]
	v_mul_f32_e32 v104, v11, v11
	v_mov_b32_e32 v99, v102
	v_mul_f32_e32 v102, v19, v19
	v_pk_fma_f32 v[102:103], v[18:19], v[18:19], v[102:103] op_sel_hi:[1,1,0]
	global_store_dwordx4 v[148:149], v[4:7], off
	v_mov_b32_e32 v103, v104
	v_pk_add_f32 v[98:99], v[98:99], v[102:103]
	global_store_dwordx4 v[84:85], v[8:11], off offset:-4096
	v_pk_add_f32 v[98:99], v[96:97], v[98:99]
	v_pk_mul_f32 v[96:97], v[100:101], v[114:115] op_sel_hi:[0,1]
	v_pk_mul_f32 v[100:101], v[100:101], v[110:111] op_sel_hi:[0,1]
	v_pk_mul_f32 v[24:25], v[100:101], v[24:25]
	v_pk_mul_f32 v[26:27], v[96:97], v[26:27]
	v_pk_fma_f32 v[20:21], v[48:49], v[24:25], v[20:21]
	v_pk_fma_f32 v[22:23], v[50:51], v[26:27], v[22:23]
	v_mul_f32_e32 v26, v20, v20
	v_pk_add_f32 v[24:25], v[162:163], v[162:163] op_sel:[0,1] op_sel_hi:[1,0]
	v_mul_f32_e32 v48, v21, v21
	v_mov_b32_e32 v25, v26
	v_pk_add_f32 v[26:27], v[134:135], v[134:135] op_sel:[0,1] op_sel_hi:[1,0]
	v_mul_f32_e32 v49, v22, v22
	v_mov_b32_e32 v27, v48
	v_pk_add_f32 v[24:25], v[24:25], v[26:27]
	v_mul_f32_e32 v26, v13, v13
	v_pk_fma_f32 v[26:27], v[12:13], v[12:13], v[26:27] op_sel_hi:[1,1,0]
	v_mul_f32_e32 v48, v15, v15
	v_mul_f32_e32 v50, v23, v23
	v_mov_b32_e32 v27, v49
	v_pk_fma_f32 v[48:49], v[14:15], v[14:15], v[48:49] op_sel_hi:[1,1,0]
	global_store_dwordx4 v[84:85], v[20:23], off
	v_mov_b32_e32 v49, v50
	v_pk_add_f32 v[26:27], v[26:27], v[48:49]
	v_lshl_add_u64 v[104:105], v[118:119], 0, s[2:3]
	v_pk_add_f32 v[24:25], v[24:25], v[26:27]
	v_mov_b32_e32 v26, v74
	v_mov_b32_e32 v27, v72
	v_mov_b32_e32 v72, v75
	v_pk_add_f32 v[26:27], v[26:27], v[72:73]
	ds_bpermute_b32 v49, v187, v27
	ds_bpermute_b32 v48, v187, v26
	s_movk_i32 s2, 0x5fff
	v_lshl_add_u64 v[84:85], v[84:85], 0, s[72:73]
	s_waitcnt lgkmcnt(0)
	v_pk_add_f32 v[26:27], v[26:27], v[48:49]
	ds_bpermute_b32 v49, v188, v27
	ds_bpermute_b32 v48, v188, v26
	s_waitcnt lgkmcnt(0)
	v_pk_add_f32 v[26:27], v[26:27], v[48:49]
	ds_bpermute_b32 v49, v189, v27
	ds_bpermute_b32 v48, v189, v26
	s_waitcnt lgkmcnt(0)
	v_pk_add_f32 v[26:27], v[26:27], v[48:49]
	ds_bpermute_b32 v49, v190, v27
	ds_bpermute_b32 v48, v190, v26
	s_waitcnt lgkmcnt(0)
	v_pk_add_f32 v[26:27], v[26:27], v[48:49]
	ds_bpermute_b32 v49, v191, v27
	ds_bpermute_b32 v48, v191, v26
	s_waitcnt lgkmcnt(0)
	v_pk_add_f32 v[26:27], v[26:27], v[48:49]
	ds_bpermute_b32 v49, v192, v27
	ds_bpermute_b32 v48, v192, v26
	s_waitcnt lgkmcnt(0)
	v_pk_add_f32 v[26:27], v[26:27], v[48:49]
	s_nop 0
	v_pk_fma_f32 v[26:27], v[26:27], s[82:83], v[116:117] op_sel_hi:[1,0,0]
	s_nop 0
	v_mul_f32_e32 v48, 0x4b800000, v27
	v_cmp_gt_f32_e64 s[4:5], s81, v27
	v_cmp_gt_f32_e32 vcc, s81, v26
	s_nop 0
	v_cndmask_b32_e64 v27, v27, v48, s[4:5]
	v_rsq_f32_e32 v27, v27
	s_nop 0
	v_mul_f32_e32 v48, 0x45800000, v27
	v_cndmask_b32_e64 v100, v27, v48, s[4:5]
	v_mul_f32_e32 v27, 0x4b800000, v26
	v_cndmask_b32_e32 v26, v26, v27, vcc
	v_rsq_f32_e32 v26, v26
	v_lshl_add_u64 v[48:49], v[104:105], 0, v[88:89]
	global_load_dwordx4 v[48:51], v[48:49], off
	v_pk_mul_f32 v[42:43], v[42:43], v[100:101] op_sel_hi:[1,0]
	v_mul_f32_e32 v27, 0x45800000, v26
	v_cndmask_b32_e32 v96, v26, v27, vcc
	v_mov_b32_e32 v26, v24
	v_mov_b32_e32 v27, v98
	v_mov_b32_e32 v98, v25
	v_pk_add_f32 v[24:25], v[26:27], v[98:99]
	ds_bpermute_b32 v27, v187, v25
	ds_bpermute_b32 v26, v187, v24
	v_pk_mul_f32 v[40:41], v[40:41], v[100:101] op_sel_hi:[1,0]
	v_pk_mul_f32 v[44:45], v[44:45], v[96:97] op_sel_hi:[1,0]
	v_pk_mul_f32 v[30:31], v[30:31], v[100:101] op_sel_hi:[1,0]
	v_pk_mul_f32 v[28:29], v[28:29], v[100:101] op_sel_hi:[1,0]
	s_waitcnt lgkmcnt(0)
	v_pk_add_f32 v[24:25], v[24:25], v[26:27]
	ds_bpermute_b32 v27, v188, v25
	ds_bpermute_b32 v26, v188, v24
	v_pk_mul_f32 v[2:3], v[2:3], v[100:101] op_sel_hi:[1,0]
	v_pk_mul_f32 v[0:1], v[0:1], v[100:101] op_sel_hi:[1,0]
	s_waitcnt lgkmcnt(0)
	v_pk_add_f32 v[24:25], v[24:25], v[26:27]
	ds_bpermute_b32 v27, v189, v25
	ds_bpermute_b32 v26, v189, v24
	s_waitcnt lgkmcnt(0)
	v_pk_add_f32 v[24:25], v[24:25], v[26:27]
	ds_bpermute_b32 v27, v190, v25
	ds_bpermute_b32 v26, v190, v24
	s_waitcnt lgkmcnt(0)
	v_pk_add_f32 v[24:25], v[24:25], v[26:27]
	ds_bpermute_b32 v27, v191, v25
	ds_bpermute_b32 v26, v191, v24
	s_waitcnt lgkmcnt(0)
	v_pk_add_f32 v[24:25], v[24:25], v[26:27]
	ds_bpermute_b32 v27, v192, v25
	ds_bpermute_b32 v26, v192, v24
	s_waitcnt lgkmcnt(0)
	v_pk_add_f32 v[24:25], v[24:25], v[26:27]
	s_nop 0
	v_pk_fma_f32 v[24:25], v[24:25], s[82:83], v[116:117] op_sel_hi:[1,0,0]
	s_nop 0
	v_mul_f32_e32 v26, 0x4b800000, v25
	v_cmp_gt_f32_e64 s[4:5], s81, v25
	v_cmp_gt_f32_e32 vcc, s81, v24
	s_nop 0
	v_cndmask_b32_e64 v25, v25, v26, s[4:5]
	v_rsq_f32_e32 v25, v25
	s_nop 0
	v_mul_f32_e32 v26, 0x45800000, v25
	v_cndmask_b32_e64 v102, v25, v26, s[4:5]
	v_mul_f32_e32 v25, 0x4b800000, v24
	v_cndmask_b32_e32 v24, v24, v25, vcc
	v_rsq_f32_e32 v24, v24
	s_mov_b64 s[4:5], 0x4000
	v_lshl_add_u64 v[106:107], v[118:119], 0, s[4:5]
	v_lshl_add_u64 v[72:73], v[106:107], 0, v[88:89]
	v_mul_f32_e32 v25, 0x45800000, v24
	v_cndmask_b32_e32 v98, v24, v25, vcc
	global_load_dwordx4 v[24:27], v[80:81], off
	v_pk_mul_f32 v[16:17], v[16:17], v[102:103] op_sel_hi:[1,0]
	global_load_dwordx4 v[72:75], v[72:73], off
	v_pk_mul_f32 v[12:13], v[12:13], v[98:99] op_sel_hi:[1,0]
	v_pk_mul_f32 v[18:19], v[18:19], v[102:103] op_sel_hi:[1,0]
	v_pk_mul_f32 v[14:15], v[14:15], v[98:99] op_sel_hi:[1,0]
	s_waitcnt vmcnt(1)
	v_pk_mul_f32 v[40:41], v[40:41], v[24:25]
	v_pk_mul_f32 v[42:43], v[42:43], v[26:27]
	s_waitcnt vmcnt(0)
	v_pk_add_f32 v[74:75], v[74:75], 1.0 op_sel_hi:[1,0]
	v_pk_add_f32 v[72:73], v[72:73], 1.0 op_sel_hi:[1,0]
	v_pk_fma_f32 v[42:43], v[42:43], v[74:75], v[50:51]
	v_pk_fma_f32 v[40:41], v[40:41], v[72:73], v[48:49]
	v_pk_mul_f32 v[44:45], v[44:45], v[24:25]
	v_cvt_pk_bf16_f32 v108, v40, v41
	v_cvt_pk_bf16_f32 v109, v42, v43
	v_add_co_u32_e32 v40, vcc, s33, v86
	v_pk_mul_f32 v[42:43], v[46:47], v[96:97] op_sel_hi:[1,0]
	s_nop 0
	v_addc_co_u32_e32 v41, vcc, -1, v87, vcc
	v_pk_mul_f32 v[42:43], v[42:43], v[26:27]
	v_pk_fma_f32 v[44:45], v[44:45], v[72:73], v[48:49]
	global_store_dwordx2 v[40:41], v[108:109], off offset:-3584
	v_pk_fma_f32 v[42:43], v[42:43], v[74:75], v[50:51]
	v_cvt_pk_bf16_f32 v44, v44, v45
	v_lshl_add_u64 v[46:47], v[106:107], 0, v[90:91]
	v_cvt_pk_bf16_f32 v45, v42, v43
	global_store_dwordx2 v[40:41], v[44:45], off offset:-1536
	v_pk_mul_f32 v[44:45], v[52:53], v[102:103] op_sel_hi:[1,0]
	v_pk_mul_f32 v[42:43], v[54:55], v[102:103] op_sel_hi:[1,0]
	v_pk_mul_f32 v[44:45], v[24:25], v[44:45]
	v_pk_mul_f32 v[42:43], v[26:27], v[42:43]
	v_pk_fma_f32 v[44:45], v[72:73], v[44:45], v[48:49]
	v_pk_fma_f32 v[42:43], v[74:75], v[42:43], v[50:51]
	v_cvt_pk_bf16_f32 v44, v44, v45
	v_cmp_lt_i32_e32 vcc, s2, v76
	v_cvt_pk_bf16_f32 v45, v42, v43
	global_store_dwordx2 v[86:87], v[44:45], off offset:-3584
	v_pk_mul_f32 v[44:45], v[56:57], v[98:99] op_sel_hi:[1,0]
	v_pk_mul_f32 v[42:43], v[58:59], v[98:99] op_sel_hi:[1,0]
	v_pk_mul_f32 v[24:25], v[24:25], v[44:45]
	v_pk_mul_f32 v[26:27], v[26:27], v[42:43]
	v_pk_fma_f32 v[24:25], v[72:73], v[24:25], v[48:49]
	v_pk_fma_f32 v[26:27], v[74:75], v[26:27], v[50:51]
	v_cvt_pk_bf16_f32 v24, v24, v25
	v_lshl_add_u64 v[42:43], v[104:105], 0, v[90:91]
	v_cvt_pk_bf16_f32 v25, v26, v27
	global_store_dwordx2 v[86:87], v[24:25], off offset:-1536
	global_load_dwordx4 v[24:27], v[80:81], off offset:1024
	s_or_b64 s[10:11], vcc, s[10:11]
	global_load_dwordx4 v[46:49], v[46:47], off
	s_waitcnt vmcnt(1)
	v_pk_mul_f32 v[28:29], v[28:29], v[24:25]
	global_load_dwordx4 v[42:45], v[42:43], off
	s_waitcnt vmcnt(1)
	v_pk_add_f32 v[48:49], v[48:49], 1.0 op_sel_hi:[1,0]
	v_pk_add_f32 v[46:47], v[46:47], 1.0 op_sel_hi:[1,0]
	v_pk_mul_f32 v[30:31], v[30:31], v[26:27]
	s_waitcnt vmcnt(0)
	v_pk_fma_f32 v[28:29], v[28:29], v[46:47], v[42:43]
	v_pk_fma_f32 v[30:31], v[30:31], v[48:49], v[44:45]
	v_cvt_pk_bf16_f32 v28, v28, v29
	s_nop 0
	v_cvt_pk_bf16_f32 v29, v30, v31
	v_pk_mul_f32 v[30:31], v[32:33], v[96:97] op_sel_hi:[1,0]
	global_store_dwordx2 v[40:41], v[28:29], off offset:-3072
	v_pk_mul_f32 v[28:29], v[34:35], v[96:97] op_sel_hi:[1,0]
	v_pk_mul_f32 v[30:31], v[30:31], v[24:25]
	v_pk_mul_f32 v[28:29], v[28:29], v[26:27]
	v_pk_fma_f32 v[30:31], v[30:31], v[46:47], v[42:43]
	v_pk_fma_f32 v[28:29], v[28:29], v[48:49], v[44:45]
	v_cvt_pk_bf16_f32 v30, v30, v31
	v_lshl_add_u64 v[32:33], v[106:107], 0, v[92:93]
	v_cvt_pk_bf16_f32 v31, v28, v29
	global_store_dwordx2 v[40:41], v[30:31], off offset:-1024
	v_pk_mul_f32 v[30:31], v[36:37], v[102:103] op_sel_hi:[1,0]
	v_pk_mul_f32 v[28:29], v[38:39], v[102:103] op_sel_hi:[1,0]
	v_pk_mul_f32 v[30:31], v[30:31], v[24:25]
	v_pk_mul_f32 v[28:29], v[28:29], v[26:27]
	v_pk_fma_f32 v[30:31], v[30:31], v[46:47], v[42:43]
	v_pk_fma_f32 v[28:29], v[28:29], v[48:49], v[44:45]
	v_cvt_pk_bf16_f32 v30, v30, v31
	v_pk_mul_f32 v[38:39], v[64:65], v[100:101] op_sel_hi:[1,0]
	v_cvt_pk_bf16_f32 v31, v28, v29
	global_store_dwordx2 v[86:87], v[30:31], off offset:-3072
	v_pk_mul_f32 v[30:31], v[68:69], v[98:99] op_sel_hi:[1,0]
	v_pk_mul_f32 v[28:29], v[70:71], v[98:99] op_sel_hi:[1,0]
	v_pk_mul_f32 v[24:25], v[30:31], v[24:25]
	v_pk_mul_f32 v[26:27], v[28:29], v[26:27]
	v_pk_fma_f32 v[24:25], v[24:25], v[46:47], v[42:43]
	v_pk_fma_f32 v[26:27], v[26:27], v[48:49], v[44:45]
	v_cvt_pk_bf16_f32 v24, v24, v25
	v_lshl_add_u64 v[28:29], v[104:105], 0, v[92:93]
	v_cvt_pk_bf16_f32 v25, v26, v27
	global_store_dwordx2 v[86:87], v[24:25], off offset:-1024
	global_load_dwordx4 v[24:27], v[80:81], off offset:2048
	v_pk_mul_f32 v[36:37], v[66:67], v[100:101] op_sel_hi:[1,0]
	global_load_dwordx4 v[32:35], v[32:33], off
	s_waitcnt vmcnt(1)
	v_pk_mul_f32 v[38:39], v[38:39], v[24:25]
	global_load_dwordx4 v[28:31], v[28:29], off
	s_waitcnt vmcnt(1)
	v_pk_add_f32 v[32:33], v[32:33], 1.0 op_sel_hi:[1,0]
	v_pk_add_f32 v[34:35], v[34:35], 1.0 op_sel_hi:[1,0]
	v_pk_mul_f32 v[36:37], v[36:37], v[26:27]
	v_pk_mul_f32 v[16:17], v[16:17], v[24:25]
	v_pk_mul_f32 v[12:13], v[12:13], v[24:25]
	v_pk_mul_f32 v[18:19], v[18:19], v[26:27]
	v_pk_mul_f32 v[14:15], v[14:15], v[26:27]
	s_waitcnt vmcnt(0)
	v_pk_fma_f32 v[38:39], v[38:39], v[32:33], v[28:29]
	v_pk_fma_f32 v[36:37], v[36:37], v[34:35], v[30:31]
	v_cvt_pk_bf16_f32 v38, v38, v39
	v_pk_fma_f32 v[16:17], v[16:17], v[32:33], v[28:29]
	v_cvt_pk_bf16_f32 v39, v36, v37
	global_store_dwordx2 v[40:41], v[38:39], off offset:-2560
	v_pk_mul_f32 v[38:39], v[60:61], v[96:97] op_sel_hi:[1,0]
	v_pk_mul_f32 v[36:37], v[62:63], v[96:97] op_sel_hi:[1,0]
	v_pk_mul_f32 v[38:39], v[38:39], v[24:25]
	v_pk_mul_f32 v[36:37], v[36:37], v[26:27]
	v_pk_fma_f32 v[38:39], v[38:39], v[32:33], v[28:29]
	v_pk_fma_f32 v[12:13], v[12:13], v[32:33], v[28:29]
	v_pk_fma_f32 v[36:37], v[36:37], v[34:35], v[30:31]
	v_cvt_pk_bf16_f32 v38, v38, v39
	v_pk_fma_f32 v[18:19], v[18:19], v[34:35], v[30:31]
	v_cvt_pk_bf16_f32 v39, v36, v37
	global_store_dwordx2 v[40:41], v[38:39], off offset:-512
	v_cvt_pk_bf16_f32 v16, v16, v17
	v_cvt_pk_bf16_f32 v17, v18, v19
	global_store_dwordx2 v[86:87], v[16:17], off offset:-2560
	v_pk_fma_f32 v[14:15], v[14:15], v[34:35], v[30:31]
	v_cvt_pk_bf16_f32 v12, v12, v13
	v_lshl_add_u64 v[24:25], v[106:107], 0, v[94:95]
	v_cvt_pk_bf16_f32 v13, v14, v15
	global_store_dwordx2 v[86:87], v[12:13], off offset:-512
	global_load_dwordx4 v[12:15], v[80:81], off offset:3072
	v_lshl_add_u64 v[16:17], v[104:105], 0, v[94:95]
	global_load_dwordx4 v[24:27], v[24:25], off
	s_waitcnt vmcnt(1)
	v_pk_mul_f32 v[0:1], v[0:1], v[12:13]
	global_load_dwordx4 v[16:19], v[16:17], off
	s_waitcnt vmcnt(1)
	v_pk_add_f32 v[26:27], v[26:27], 1.0 op_sel_hi:[1,0]
	v_pk_add_f32 v[24:25], v[24:25], 1.0 op_sel_hi:[1,0]
	v_pk_mul_f32 v[2:3], v[2:3], v[14:15]
	s_waitcnt vmcnt(0)
	v_pk_fma_f32 v[0:1], v[0:1], v[24:25], v[16:17]
	v_pk_fma_f32 v[2:3], v[2:3], v[26:27], v[18:19]
	v_cvt_pk_bf16_f32 v0, v0, v1
	s_nop 0
	v_cvt_pk_bf16_f32 v1, v2, v3
	v_pk_mul_f32 v[2:3], v[4:5], v[96:97] op_sel_hi:[1,0]
	global_store_dwordx2 v[40:41], v[0:1], off offset:-2048
	v_pk_mul_f32 v[0:1], v[6:7], v[96:97] op_sel_hi:[1,0]
	v_pk_mul_f32 v[2:3], v[2:3], v[12:13]
	v_pk_mul_f32 v[0:1], v[0:1], v[14:15]
	v_pk_fma_f32 v[2:3], v[2:3], v[24:25], v[16:17]
	v_pk_fma_f32 v[0:1], v[0:1], v[26:27], v[18:19]
	v_cvt_pk_bf16_f32 v2, v2, v3
	s_nop 0
	v_cvt_pk_bf16_f32 v3, v0, v1
	global_store_dwordx2 v[86:87], v[2:3], off offset:-4096
	v_pk_mul_f32 v[2:3], v[8:9], v[102:103] op_sel_hi:[1,0]
	v_pk_mul_f32 v[0:1], v[10:11], v[102:103] op_sel_hi:[1,0]
	v_pk_mul_f32 v[2:3], v[2:3], v[12:13]
	v_pk_mul_f32 v[0:1], v[0:1], v[14:15]
	v_pk_fma_f32 v[2:3], v[2:3], v[24:25], v[16:17]
	v_pk_fma_f32 v[0:1], v[0:1], v[26:27], v[18:19]
	v_cvt_pk_bf16_f32 v2, v2, v3
	s_nop 0
	v_cvt_pk_bf16_f32 v3, v0, v1
	global_store_dwordx2 v[86:87], v[2:3], off offset:-2048
	v_pk_mul_f32 v[2:3], v[20:21], v[98:99] op_sel_hi:[1,0]
	v_pk_mul_f32 v[0:1], v[22:23], v[98:99] op_sel_hi:[1,0]
	v_pk_mul_f32 v[2:3], v[2:3], v[12:13]
	v_pk_mul_f32 v[0:1], v[0:1], v[14:15]
	v_pk_fma_f32 v[2:3], v[2:3], v[24:25], v[16:17]
	v_pk_fma_f32 v[0:1], v[0:1], v[26:27], v[18:19]
	v_cvt_pk_bf16_f32 v2, v2, v3
	s_nop 0
	v_cvt_pk_bf16_f32 v3, v0, v1
	global_store_dwordx2 v[86:87], v[2:3], off
	v_lshl_add_u64 v[86:87], v[86:87], 0, s[76:77]
	s_andn2_b64 exec, exec, s[10:11]
	s_cbranch_execnz .LBB0_1534
